# in-proj K loops rotated by half a K block (previous block second-step MFMAs run under the post-barrier fragment reads), DMA pieces between MFMAs; KIND0 attention loop DMA pieces between QK MFMAs
# speedup vs baseline: 1.2137x; 1.0117x over previous
; DI int otid() { int t = threadIdx.x; asm volatile("" : "+v"(t)); return t; }
; template <int KIND>
; DI void attn_unit(const Params& p, int l, int b, int head, int qt, int qcol, int kcol, int vfeat, int gcol, int mixcol,
;                   int t1, int n1, int t2, int n2, char* smem) {
;     const int tid = otid(), lane = tid & 63, wave = tid >> 6, r = lane & 31, h = lane >> 5;
;     const int tq = qt * 128 + 32 * wave + r;
;     const size_t qrow = (size_t)b * TPB + tq;
;     const bf16_t* kbase = p.qkv + ((size_t)(kcol >> 6) * NTOK + (size_t)b * TPB) * 64;
;     const bf16_t* vbase = p.vT + ((size_t)b * 12 + (vfeat >> 6)) * 36 * 4096;
;     const int nt = n1 + n2;
;     bf16x8 qf[4];
;     {
;         const bf16_t* qp = p.qkv + ((size_t)(qcol >> 6) * NTOK + qrow) * 64 + 8 * h;
; #pragma unroll
;         for (int s = 0; s < 4; ++s) qf[s] = *(const bf16x8*)(qp + 16 * s);
;     }
;     int nrow = 0, r0w = 0, qc = 0, c0 = 0;
;     if (KIND == 2) {
;         nrow = 2 * qt + (wave >> 1); r0w = min(max(nrow - 4, 0), 24);
;         qc = 32 * (wave & 1) + r; c0 = min(max(qc - 8, 0), 48);
;         float* bias = (float*)(smem + ATT_BIAS);
;         for (int i = tid; i < 15 * 32; i += NTHREADS) { const int rr = i >> 5, cc = i & 31; bias[i] = cc < 31 ? p.rpb[((size_t)l * 6 + head) * 465 + rr * 31 + cc] * LOG2E : -INFINITY; }
;     }
;     int bcol[2][16];
;     if (KIND == 2) {
; #pragma unroll
;         for (int t = 0; t < 2; ++t)
; #pragma unroll
;             for (int e = 0; e < 16; ++e) {
;                 const int kc = 32 * t + crow(e, h);
;                 bcol[t][e] = ((unsigned)(kc - c0) < 16u) ? (kc - qc + 15) * 4 : 31 * 4;
;             }
;     }
;     f32x16 O0[2], O1[2];
; #pragma unroll
;     for (int t = 0; t < 2; ++t)
; #pragma unroll
;         for (int e = 0; e < 16; ++e) { O0[t][e] = 0.f; O1[t][e] = 0.f; }
;     float l0 = 0.f, l1 = 0.f;
;     const float zb = p.lam[8 + l * 4 + ((KIND == 1 && qcol >= 2048) ? 3 : KIND)];
;     f32x16 cz;
; #pragma unroll
;     for (int e = 0; e < 16; ++e) cz[e] = -zb;
;     const int kvoff = (8 * wave + (lane >> 3)) * 64 + (((lane & 7) ^ (((wave & 1) << 2) | (lane >> 4))) << 3);
;     const int xr = (r >> 1) & 7;
;     __syncthreads();
;     KV_ISSUE(t1, 0);
;     if (nt > 1) KV_ISSUE((1 < n1) ? t1 + 1 : t2 + (1 - n1), 1);
;     int sc = 0, sn = 2;
.LBB0_81:
	s_and_b32 s6, s8, 3
	s_mul_i32 s8, s6, 0x4800
	s_lshl_b32 s7, s7, 7
	s_mul_i32 s29, s35, 0x900
	s_add_i32 s5, s8, 0x12000
	s_mul_hi_i32 s9, s35, 0x900
	s_add_u32 s56, s29, s5
	s_mul_i32 s34, s35, 12
	v_mov_b32_e32 v23, v200
	s_addc_u32 s57, s9, 0
	s_mul_hi_i32 s5, s35, 12
	s_or_b32 s34, s34, s6
	s_load_dwordx4 s[40:43], s[0:1], 0xc0
	s_load_dwordx2 s[50:51], s[0:1], 0xf8
	v_ashrrev_i32_e32 v16, 6, v23
	s_mul_i32 s53, s34, 0x48000
	s_mul_hi_u32 s34, s34, 0x48000
	s_mul_i32 s5, s5, 0x48000
	v_and_b32_e32 v22, 31, v23
	v_lshl_add_u32 v0, v16, 5, s7
	s_lshl_b64 s[56:57], s[56:57], 7
	s_add_i32 s5, s34, s5
	v_or_b32_e32 v0, v0, v22
	s_add_u32 s58, s29, s8
	v_ashrrev_i32_e32 v1, 31, v0
	s_addc_u32 s59, s9, 0
	v_lshl_add_u64 v[0:1], s[58:59], 0, v[0:1]
	s_waitcnt lgkmcnt(0)
	s_add_u32 s58, s40, s56
	v_bfe_u32 v214, v23, 5, 1
	v_lshlrev_b64 v[0:1], 7, v[0:1]
	s_addc_u32 s59, s41, s57
	s_lshl_b64 s[56:57], s[48:49], 2
	v_lshl_add_u64 v[0:1], s[40:41], 0, v[0:1]
	v_lshlrev_b32_e32 v192, 4, v214
	s_add_u32 s56, s50, s56
	v_lshl_add_u64 v[0:1], v[0:1], 0, v[192:193]
	s_addc_u32 s57, s51, s57
	global_load_dwordx4 v[152:155], v[0:1], off
	global_load_dwordx4 v[144:147], v[0:1], off offset:32
	global_load_dwordx4 v[156:159], v[0:1], off offset:64
	global_load_dwordx4 v[148:151], v[0:1], off offset:96
	v_lshlrev_b32_e32 v17, 9, v16
	global_load_dword v0, v193, s[56:57] offset:32
	v_lshlrev_b32_e32 v18, 3, v23
	s_movk_i32 s56, 0x1c0
	v_lshlrev_b32_e32 v16, 2, v16
	v_and_or_b32 v17, v18, s56, v17
	v_and_b32_e32 v18, 7, v23
	v_and_b32_e32 v16, 4, v16
	v_bfe_u32 v19, v23, 4, 2
	s_add_u32 s53, s42, s53
	v_bitop3_b32 v16, v16, v18, v19 bitop3:0x36
	s_addc_u32 s5, s43, s5
	v_lshl_or_b32 v16, v16, 3, v17
	s_lshl_b32 s4, s4, 13
	s_add_u32 s56, s58, s4
	v_ashrrev_i32_e32 v17, 31, v16
	s_addc_u32 s57, s59, 0
	v_lshlrev_b64 v[16:17], 1, v[16:17]
	v_lshl_add_u64 v[20:21], s[56:57], 0, v[16:17]
	s_add_u32 s56, s53, s4
	v_lshl_add_u32 v220, v23, 4, 32
	v_lshrrev_b32_e32 v28, 1, v23
	v_bfe_u32 v29, v23, 1, 3
	s_addc_u32 s57, s5, 0
	v_readfirstlane_b32 s5, v220
	v_add_u32_e32 v23, 0x1000, v220
	s_mov_b32 m0, s5
	v_readfirstlane_b32 s5, v23
	v_add_u32_e32 v23, 0x2000, v220
	s_barrier
	global_load_lds_dwordx4 v[20:21], off
	v_lshl_add_u64 v[24:25], v[20:21], 0, s[26:27]
	s_mov_b32 m0, s5
	v_readfirstlane_b32 s5, v23
	v_add_u32_e32 v23, 0x3000, v220
	v_lshl_add_u64 v[18:19], s[56:57], 0, v[16:17]
	global_load_lds_dwordx4 v[24:25], off
	s_mov_b32 m0, s5
	v_readfirstlane_b32 s5, v23
	v_add_u32_e32 v23, 0x4000, v220
	global_load_lds_dwordx4 v[18:19], off
	v_lshl_add_u64 v[24:25], v[18:19], 0, s[26:27]
	s_mov_b32 m0, s5
	v_readfirstlane_b32 s5, v23
	v_add_u32_e32 v23, 0x5000, v220
	global_load_lds_dwordx4 v[24:25], off
	v_lshl_add_u64 v[24:25], v[20:21], 0, s[16:17]
	s_mov_b32 m0, s5
	v_readfirstlane_b32 s5, v23
	global_load_lds_dwordx4 v[24:25], off
	v_lshl_add_u64 v[20:21], v[20:21], 0, s[90:91]
	s_mov_b32 m0, s5
	v_lshl_add_u64 v[26:27], v[18:19], 0, s[16:17]
	global_load_lds_dwordx4 v[20:21], off
	v_add_u32_e32 v20, 0x6000, v220
	v_lshl_add_u64 v[18:19], v[18:19], 0, s[90:91]
	v_readfirstlane_b32 s5, v20
	v_add_u32_e32 v20, 0x7000, v220
	s_mov_b32 m0, s5
	v_readfirstlane_b32 s5, v20
	global_load_lds_dwordx4 v[26:27], off
	s_mov_b32 m0, s5
	s_lshl_b32 s5, s52, 13
	global_load_lds_dwordx4 v[18:19], off
	s_add_u32 s52, s5, 0x2000
	s_mul_i32 s53, s35, 0x360000
	s_mul_i32 s56, s6, 0x48000
	s_mul_hi_i32 s5, s35, 0x360000
	s_add_u32 s53, s53, s56
	s_addc_u32 s5, s5, 0
	s_add_u32 s53, s53, s4
	s_addc_u32 s5, s5, 0
	s_add_u32 s42, s42, s53
	s_addc_u32 s43, s43, s5
	v_lshl_add_u64 v[196:197], s[42:43], 0, v[16:17]
	s_mul_i32 s5, s6, 0x240000
	s_mul_hi_i32 s42, s35, 0x48000
	s_mul_i32 s35, s35, 0x48000
	s_add_u32 s5, s5, s35
	s_addc_u32 s35, 0, s42
	s_add_u32 s4, s5, s4
	v_bitop3_b32 v18, v214, v28, 7 bitop3:0x78
	s_addc_u32 s5, s35, 0
	v_lshlrev_b32_e32 v219, 4, v18
	v_bitop3_b32 v18, v214, v29, 2 bitop3:0x36
	s_add_u32 s4, s40, s4
	v_lshlrev_b32_e32 v218, 4, v18
	v_bitop3_b32 v18, v214, v29, 4 bitop3:0x36
	s_addc_u32 s5, s41, s5
	s_waitcnt vmcnt(0)
	v_xor_b32_e32 v0, 0x80000000, v0
	v_lshlrev_b32_e32 v217, 7, v22
	v_lshlrev_b32_e32 v216, 4, v18
	v_bitop3_b32 v18, v214, v29, 6 bitop3:0x36
	v_lshl_add_u64 v[198:199], s[4:5], 0, v[16:17]
	v_mov_b32_e32 v16, 0
	s_mov_b32 s34, 2
	v_mov_b32_e32 v1, v0
	v_mov_b32_e32 v2, v0
	v_mov_b32_e32 v3, v0
	v_mov_b32_e32 v4, v0
	v_mov_b32_e32 v5, v0
	v_mov_b32_e32 v6, v0
	v_mov_b32_e32 v7, v0
	v_mov_b32_e32 v8, v0
	v_mov_b32_e32 v9, v0
	v_mov_b32_e32 v10, v0
	v_mov_b32_e32 v11, v0
	v_mov_b32_e32 v12, v0
	v_mov_b32_e32 v13, v0
	v_mov_b32_e32 v14, v0
	v_mov_b32_e32 v15, v0
	v_lshlrev_b32_e32 v215, 4, v18
	v_add_u32_e32 v221, 32, v217
	s_mov_b32 s35, 0
	s_mov_b64 s[4:5], 0
	v_mov_b32_e32 v17, v16
	v_mov_b32_e32 v18, v16
	v_mov_b32_e32 v19, v16
	v_mov_b32_e32 v20, v16
	v_mov_b32_e32 v21, v16
	v_mov_b32_e32 v22, v16
	v_mov_b32_e32 v23, v16
	v_mov_b32_e32 v24, v16
	v_mov_b32_e32 v25, v16
	v_mov_b32_e32 v26, v16
	v_mov_b32_e32 v27, v16
	v_mov_b32_e32 v28, v16
	v_mov_b32_e32 v29, v16
	v_mov_b32_e32 v30, v16
	v_mov_b32_e32 v31, v16
	v_mov_b32_e32 v48, v16
	v_mov_b32_e32 v49, v16
	v_mov_b32_e32 v50, v16
	v_mov_b32_e32 v51, v16
	v_mov_b32_e32 v52, v16
	v_mov_b32_e32 v53, v16
	v_mov_b32_e32 v54, v16
	v_mov_b32_e32 v55, v16
	v_mov_b32_e32 v56, v16
	v_mov_b32_e32 v57, v16
	v_mov_b32_e32 v58, v16
	v_mov_b32_e32 v59, v16
	v_mov_b32_e32 v60, v16
	v_mov_b32_e32 v61, v16
	v_mov_b32_e32 v62, v16
	v_mov_b32_e32 v63, v16
	v_mov_b32_e32 v32, v16
	v_mov_b32_e32 v33, v16
	v_mov_b32_e32 v34, v16
	v_mov_b32_e32 v35, v16
	v_mov_b32_e32 v36, v16
	v_mov_b32_e32 v37, v16
	v_mov_b32_e32 v38, v16
	v_mov_b32_e32 v39, v16
	v_mov_b32_e32 v40, v16
	v_mov_b32_e32 v41, v16
	v_mov_b32_e32 v42, v16
	v_mov_b32_e32 v43, v16
	v_mov_b32_e32 v44, v16
	v_mov_b32_e32 v45, v16
	v_mov_b32_e32 v46, v16
	v_mov_b32_e32 v47, v16
	v_mov_b32_e32 v64, v16
	v_mov_b32_e32 v65, v16
	v_mov_b32_e32 v66, v16
	v_mov_b32_e32 v67, v16
	v_mov_b32_e32 v68, v16
	v_mov_b32_e32 v69, v16
	v_mov_b32_e32 v70, v16
	v_mov_b32_e32 v71, v16
	v_mov_b32_e32 v72, v16
	v_mov_b32_e32 v73, v16
	v_mov_b32_e32 v74, v16
	v_mov_b32_e32 v75, v16
	v_mov_b32_e32 v76, v16
	v_mov_b32_e32 v77, v16
	v_mov_b32_e32 v78, v16
	v_mov_b32_e32 v79, v16
	v_mov_b32_e32 v194, v16
	v_mov_b32_e32 v195, v16
	v_readfirstlane_b32 s100, v220
; DI void softmax_tile(f32x16 (&S)[2], float& lsum) {
;     f2_t ps = {0.f, 0.f};
; #pragma unroll
;     for (int t = 0; t < 2; ++t)
; #pragma unroll
;         for (int e = 0; e < 16; e += 2) {
;             f2_t pv; pv.x = __builtin_amdgcn_exp2f(S[t][e]); pv.y = __builtin_amdgcn_exp2f(S[t][e + 1]);
;             S[t][e] = pv.x; S[t][e + 1] = pv.y;
;             ps += pv;
;         }
;     lsum += ps.x + ps.y;
; }
; DI void pv_tile(const f32x16 (&S)[2], f32x16 (&O)[2], const bf16x8 (&vf)[8]) {
; #pragma unroll
;     for (int s = 0; s < 4; ++s) {
;         const bf16x8 pf = pack8(S[s >> 1], s & 1);
; template <int KIND>
; DI void attn_unit(const Params& p, int l, int b, int head, int qt, int qcol, int kcol, int vfeat, int gcol, int mixcol,
;                   int t1, int n1, int t2, int n2, char* smem) {
;     ...
;     for (int it = 0; it < nt; ++it) {
;         const int tile = (it < n1) ? t1 + it : t2 + (it - n1);
;         if (it + 1 < nt) asm volatile("s_waitcnt vmcnt(4)" ::: "memory"); else asm volatile("s_waitcnt vmcnt(0)" ::: "memory");
;         __builtin_amdgcn_s_barrier();
;         const char* sk = smem + sc * ATT_SLOT;
;         const char* sv = sk + ATT_V;
;         bool active = true;
;         if (KIND == 2 && tile < 32) active = (tile >= r0w) && (tile < r0w + 8);
;         bf16x8 kf[8], vf[8];
;         if (active) {
; #pragma unroll
;             for (int s = 0; s < 4; ++s)
; #pragma unroll
;                 for (int t = 0; t < 2; ++t) kf[2 * s + t] = *(const bf16x8*)(sk + (32 * t + r) * 128 + (((2 * s + h) ^ xr) << 4));
;         }
;         __builtin_amdgcn_sched_barrier(0);
;         if (it + 2 < nt) { const int nx = (it + 2 < n1) ? t1 + it + 2 : t2 + (it + 2 - n1); KV_ISSUE(nx, sn); }
;         sc = (sc == 2) ? 0 : sc + 1; sn = (sn == 2) ? 0 : sn + 1;
;         __builtin_amdgcn_sched_barrier(0);
;         if (active) {
;     ...
;             if (KIND == 0) {
;                 f32x16 S0[2], S1[2];
; #pragma unroll
;                 for (int t = 0; t < 2; ++t) { S0[t] = MFMA(kf[t], qf[0], cz); S1[t] = MFMA(kf[4 + t], qf[2], cz); }
; #pragma unroll
;                 for (int t = 0; t < 2; ++t) { S0[t] = MFMA(kf[2 + t], qf[1], S0[t]); S1[t] = MFMA(kf[6 + t], qf[3], S1[t]); }
;                 LOAD_VF();
;                 softmax_tile(S0, l0);
;                 pv_tile(S0, O0, vf);
;                 softmax_tile(S1, l1);
;                 pv_tile(S1, O1, vf);
.LBB0_82:
	v_lshl_add_u32 v92, s35, 14, v221
	v_add_u32_e32 v180, v92, v219
	v_add_u32_e32 v222, v92, v218
	v_add_u32_e32 v223, v92, v216
	v_add_u32_e32 v224, v92, v215
	s_waitcnt vmcnt(4)
	s_barrier
	ds_read_b128 v[80:83], v180
	ds_read_b128 v[84:87], v180 offset:4096
	ds_read_b128 v[160:163], v222
	ds_read_b128 v[164:167], v222 offset:4096
	ds_read_b128 v[88:91], v223
	ds_read_b128 v[168:171], v223 offset:4096
	ds_read_b128 v[172:175], v224
	ds_read_b128 v[176:179], v224 offset:4096
	v_lshl_add_u64 v[226:227], v[198:199], 0, s[4:5]
	s_mov_b64 s[42:43], 0x904000
	v_lshl_add_u64 v[228:229], v[226:227], 0, s[42:43]
	s_mov_b64 s[42:43], 0x905000
	v_lshl_add_u64 v[226:227], v[226:227], 0, s[42:43]
	v_lshl_add_u64 v[230:231], v[196:197], 0, s[4:5]
	v_lshl_add_u64 v[232:233], v[230:231], 0, s[92:93]
	v_lshl_add_u64 v[230:231], v[230:231], 0, s[94:95]
	s_lshl_b32 s101, s34, 14
	s_add_i32 s101, s101, s100
	s_add_i32 s42, s35, 1
	s_cmp_lg_u32 s35, 2
	s_cselect_b32 s35, s42, 0
	s_add_i32 s42, s34, 1
	s_mov_b32 m0, s101
	s_waitcnt lgkmcnt(0)
	v_mfma_f32_32x32x16_bf16 v[128:143], v[80:83], v[152:155], v[0:15]
	global_load_lds_dwordx4 v[228:229], off
	s_add_u32 m0, s101, 0x1000
	v_mfma_f32_32x32x16_bf16 v[96:111], v[88:91], v[156:159], v[0:15]
	global_load_lds_dwordx4 v[226:227], off
	s_add_u32 m0, s101, 0x2000
	v_mfma_f32_32x32x16_bf16 v[112:127], v[84:87], v[152:155], v[0:15]
	global_load_lds_dwordx4 v[232:233], off
	s_add_u32 m0, s101, 0x3000
	v_mfma_f32_32x32x16_bf16 v[80:95], v[168:171], v[156:159], v[0:15]
	global_load_lds_dwordx4 v[230:231], off
	v_mfma_f32_32x32x16_bf16 v[128:143], v[160:163], v[144:147], v[128:143]
	v_mfma_f32_32x32x16_bf16 v[96:111], v[172:175], v[148:151], v[96:111]
	v_mfma_f32_32x32x16_bf16 v[112:127], v[164:167], v[144:147], v[112:127]
	v_mfma_f32_32x32x16_bf16 v[80:95], v[176:179], v[148:151], v[80:95]
	ds_read_b128 v[188:191], v180 offset:8192
	ds_read_b128 v[184:187], v180 offset:12288
	ds_read_b128 v[180:183], v222 offset:8192
	ds_read_b128 v[176:179], v222 offset:12288
	ds_read_b128 v[172:175], v223 offset:8192
	ds_read_b128 v[168:171], v223 offset:12288
	ds_read_b128 v[164:167], v224 offset:8192
	ds_read_b128 v[160:163], v224 offset:12288
	s_cmp_lg_u32 s34, 2
	s_cselect_b32 s34, s42, 0
	v_exp_f32_e32 v128, v128
	v_exp_f32_e32 v129, v129
	v_exp_f32_e32 v130, v130
	v_exp_f32_e32 v131, v131
	v_exp_f32_e32 v132, v132
	v_exp_f32_e32 v133, v133
	v_exp_f32_e32 v134, v134
	v_exp_f32_e32 v135, v135
	v_add_f32_e64 v222, v128, 0
	v_add_f32_e64 v223, v129, 0
	v_cvt_pk_bf16_f32 v128, v128, v129
	v_add_f32_e64 v222, v130, v222
	v_add_f32_e64 v223, v131, v223
	v_cvt_pk_bf16_f32 v129, v130, v131
	v_cvt_pk_bf16_f32 v130, v132, v133
	v_cvt_pk_bf16_f32 v131, v134, v135
	v_add_f32_e64 v222, v132, v222
	v_add_f32_e64 v223, v133, v223
	v_exp_f32_e32 v136, v136
	s_waitcnt lgkmcnt(0)
	v_mfma_f32_32x32x16_bf16 v[48:63], v[188:191], v[128:131], v[48:63]
	v_exp_f32_e32 v137, v137
	v_exp_f32_e32 v138, v138
	v_exp_f32_e32 v139, v139
	v_exp_f32_e32 v132, v140
	v_exp_f32_e32 v133, v141
	v_exp_f32_e32 v140, v142
	v_exp_f32_e32 v141, v143
	v_mfma_f32_32x32x16_bf16 v[32:47], v[184:187], v[128:131], v[32:47]
	v_add_f32_e64 v134, v134, v222
	v_add_f32_e64 v135, v135, v223
	v_cvt_pk_bf16_f32 v128, v136, v137
	v_cvt_pk_bf16_f32 v129, v138, v139
	v_cvt_pk_bf16_f32 v130, v132, v133
	v_cvt_pk_bf16_f32 v131, v140, v141
	v_add_f32_e64 v134, v136, v134
	v_add_f32_e64 v135, v137, v135
	v_exp_f32_e32 v112, v112
	v_mfma_f32_32x32x16_bf16 v[48:63], v[180:183], v[128:131], v[48:63]
	v_add_f32_e64 v134, v138, v134
	v_add_f32_e64 v135, v139, v135
	v_exp_f32_e32 v113, v113
	v_add_f32_e64 v134, v132, v134
	v_add_f32_e64 v135, v133, v135
	v_exp_f32_e32 v116, v116
	v_add_f32_e64 v132, v140, v134
	v_add_f32_e64 v133, v141, v135
	v_exp_f32_e32 v134, v114
	v_exp_f32_e32 v135, v115
	v_mfma_f32_32x32x16_bf16 v[32:47], v[176:179], v[128:131], v[32:47]
	v_exp_f32_e32 v117, v117
	v_exp_f32_e32 v118, v118
	v_exp_f32_e32 v119, v119
	v_add_f32_e64 v132, v112, v132
	v_add_f32_e64 v133, v113, v133
	v_cvt_pk_bf16_f32 v112, v112, v113
	v_cvt_pk_bf16_f32 v113, v134, v135
	v_cvt_pk_bf16_f32 v114, v116, v117
	v_cvt_pk_bf16_f32 v115, v118, v119
	v_add_f32_e64 v128, v134, v132
	v_add_f32_e64 v129, v135, v133
	v_exp_f32_e32 v120, v120
	v_mfma_f32_32x32x16_bf16 v[48:63], v[172:175], v[112:115], v[48:63]
	v_add_f32_e64 v116, v116, v128
	v_add_f32_e64 v117, v117, v129
	v_exp_f32_e32 v121, v121
	v_add_f32_e64 v116, v118, v116
	v_add_f32_e64 v117, v119, v117
	v_exp_f32_e32 v118, v122
	v_exp_f32_e32 v119, v123
	v_exp_f32_e32 v122, v124
	v_exp_f32_e32 v123, v125
	v_mfma_f32_32x32x16_bf16 v[32:47], v[168:171], v[112:115], v[32:47]
	v_exp_f32_e32 v124, v126
	v_exp_f32_e32 v125, v127
	v_exp_f32_e32 v96, v96
	v_exp_f32_e32 v97, v97
	v_exp_f32_e32 v98, v98
	v_exp_f32_e32 v99, v99
	v_exp_f32_e32 v100, v100
	v_exp_f32_e32 v101, v101
	v_exp_f32_e32 v102, v102
	v_exp_f32_e32 v103, v103
	v_cvt_pk_bf16_f32 v112, v120, v121
	v_cvt_pk_bf16_f32 v113, v118, v119
	v_cvt_pk_bf16_f32 v114, v122, v123
	v_cvt_pk_bf16_f32 v115, v124, v125
	v_exp_f32_e32 v104, v104
	v_exp_f32_e32 v105, v105
	v_mfma_f32_32x32x16_bf16 v[48:63], v[164:167], v[112:115], v[48:63]
	v_exp_f32_e32 v106, v106
	v_exp_f32_e32 v107, v107
	v_exp_f32_e32 v108, v108
	v_exp_f32_e32 v109, v109
	v_exp_f32_e32 v84, v84
	v_exp_f32_e32 v85, v85
	v_exp_f32_e32 v86, v86
	v_mfma_f32_32x32x16_bf16 v[32:47], v[160:163], v[112:115], v[32:47]
	v_add_f32_e64 v112, v96, 0
	v_add_f32_e64 v113, v97, 0
	v_cvt_pk_bf16_f32 v96, v96, v97
	v_add_f32_e64 v112, v98, v112
	v_add_f32_e64 v113, v99, v113
	v_cvt_pk_bf16_f32 v97, v98, v99
	v_cvt_pk_bf16_f32 v98, v100, v101
; DI void softmax_tile(f32x16 (&S)[2], float& lsum) {
;     f2_t ps = {0.f, 0.f};
; #pragma unroll
;     for (int t = 0; t < 2; ++t)
; #pragma unroll
;         for (int e = 0; e < 16; e += 2) {
;             f2_t pv; pv.x = __builtin_amdgcn_exp2f(S[t][e]); pv.y = __builtin_amdgcn_exp2f(S[t][e + 1]);
;             S[t][e] = pv.x; S[t][e + 1] = pv.y;
;             ps += pv;
;         }
;     lsum += ps.x + ps.y;
; }
; DI void pv_tile(const f32x16 (&S)[2], f32x16 (&O)[2], const bf16x8 (&vf)[8]) {
; #pragma unroll
;     for (int s = 0; s < 4; ++s) {
;         const bf16x8 pf = pack8(S[s >> 1], s & 1);
; template <int KIND>
; DI void attn_unit(const Params& p, int l, int b, int head, int qt, int qcol, int kcol, int vfeat, int gcol, int mixcol,
;                   int t1, int n1, int t2, int n2, char* smem) {
;     ...
;     for (int it = 0; it < nt; ++it) {
;         const int tile = (it < n1) ? t1 + it : t2 + (it - n1);
;         if (it + 1 < nt) asm volatile("s_waitcnt vmcnt(4)" ::: "memory"); else asm volatile("s_waitcnt vmcnt(0)" ::: "memory");
;         __builtin_amdgcn_s_barrier();
;         const char* sk = smem + sc * ATT_SLOT;
;         const char* sv = sk + ATT_V;
;         bool active = true;
;         if (KIND == 2 && tile < 32) active = (tile >= r0w) && (tile < r0w + 8);
;         bf16x8 kf[8], vf[8];
;         if (active) {
; #pragma unroll
;             for (int s = 0; s < 4; ++s)
; #pragma unroll
;                 for (int t = 0; t < 2; ++t) kf[2 * s + t] = *(const bf16x8*)(sk + (32 * t + r) * 128 + (((2 * s + h) ^ xr) << 4));
;         }
;         __builtin_amdgcn_sched_barrier(0);
;         if (it + 2 < nt) { const int nx = (it + 2 < n1) ? t1 + it + 2 : t2 + (it + 2 - n1); KV_ISSUE(nx, sn); }
;         sc = (sc == 2) ? 0 : sc + 1; sn = (sn == 2) ? 0 : sn + 1;
;         __builtin_amdgcn_sched_barrier(0);
;         if (active) {
;     ...
;             if (KIND == 0) {
;                 f32x16 S0[2], S1[2];
; #pragma unroll
;                 for (int t = 0; t < 2; ++t) { S0[t] = MFMA(kf[t], qf[0], cz); S1[t] = MFMA(kf[4 + t], qf[2], cz); }
; #pragma unroll
;                 for (int t = 0; t < 2; ++t) { S0[t] = MFMA(kf[2 + t], qf[1], S0[t]); S1[t] = MFMA(kf[6 + t], qf[3], S1[t]); }
;                 LOAD_VF();
;                 softmax_tile(S0, l0);
;                 pv_tile(S0, O0, vf);
;                 softmax_tile(S1, l1);
;                 pv_tile(S1, O1, vf);
	v_cvt_pk_bf16_f32 v99, v102, v103
	v_add_f32_e64 v112, v100, v112
	v_add_f32_e64 v113, v101, v113
	v_exp_f32_e32 v100, v110
	v_mfma_f32_32x32x16_bf16 v[64:79], v[188:191], v[96:99], v[64:79]
	v_add_f32_e64 v112, v102, v112
	v_add_f32_e64 v113, v103, v113
	v_exp_f32_e32 v101, v111
	v_add_f32_e64 v112, v104, v112
	v_add_f32_e64 v113, v105, v113
	v_exp_f32_e32 v102, v80
	v_exp_f32_e32 v103, v81
	v_add_f32_e64 v112, v106, v112
	v_add_f32_e64 v113, v107, v113
	v_exp_f32_e32 v87, v87
	v_mfma_f32_32x32x16_bf16 v[16:31], v[184:187], v[96:99], v[16:31]
	v_add_f32_e64 v80, v108, v112
	v_add_f32_e64 v81, v109, v113
	v_exp_f32_e32 v98, v82
	v_add_f32_e64 v80, v100, v80
	v_add_f32_e64 v81, v101, v81
	v_exp_f32_e32 v99, v83
	v_add_f32_e64 v96, v102, v80
	v_add_f32_e64 v97, v103, v81
	v_cvt_pk_bf16_f32 v80, v104, v105
	v_cvt_pk_bf16_f32 v81, v106, v107
	v_cvt_pk_bf16_f32 v82, v108, v109
	v_cvt_pk_bf16_f32 v83, v100, v101
	v_exp_f32_e32 v88, v88
	v_exp_f32_e32 v89, v89
	v_mfma_f32_32x32x16_bf16 v[64:79], v[180:183], v[80:83], v[64:79]
	v_add_f32_e64 v96, v98, v96
	v_add_f32_e64 v97, v99, v97
	v_add_f32_e64 v116, v120, v116
	v_add_f32_e64 v117, v121, v117
	s_add_u32 s4, s4, 0x2000
	v_add_f32_e64 v116, v118, v116
	v_add_f32_e64 v117, v119, v117
	s_addc_u32 s5, s5, 0
	v_add_f32_e64 v116, v122, v116
	v_add_f32_e64 v117, v123, v117
	s_cmp_eq_u32 s52, s4
	v_mfma_f32_32x32x16_bf16 v[16:31], v[176:179], v[80:83], v[16:31]
	v_add_f32_e64 v80, v84, v96
	v_add_f32_e64 v81, v85, v97
	v_cvt_pk_bf16_f32 v82, v84, v85
	v_add_f32_e64 v80, v86, v80
	v_add_f32_e64 v81, v87, v81
	v_cvt_pk_bf16_f32 v83, v86, v87
	v_add_f32_e64 v96, v88, v80
	v_add_f32_e64 v97, v89, v81
	v_cvt_pk_bf16_f32 v80, v102, v103
	v_cvt_pk_bf16_f32 v81, v98, v99
	v_exp_f32_e32 v84, v90
	v_exp_f32_e32 v85, v91
	v_mfma_f32_32x32x16_bf16 v[64:79], v[172:175], v[80:83], v[64:79]
	v_exp_f32_e32 v86, v92
	v_exp_f32_e32 v87, v93
	v_exp_f32_e32 v90, v94
	v_exp_f32_e32 v91, v95
	v_add_f32_e64 v92, v84, v96
	v_add_f32_e64 v93, v85, v97
	v_add_f32_e64 v116, v124, v116
	v_add_f32_e64 v117, v125, v117
	v_mfma_f32_32x32x16_bf16 v[16:31], v[168:171], v[80:83], v[16:31]
	v_add_f32_e64 v80, v86, v92
	v_add_f32_e64 v81, v87, v93
	v_cvt_pk_bf16_f32 v82, v86, v87
	v_add_f32_e64 v92, v90, v80
	v_add_f32_e64 v93, v91, v81
	v_cvt_pk_bf16_f32 v80, v88, v89
	v_cvt_pk_bf16_f32 v81, v84, v85
	v_cvt_pk_bf16_f32 v83, v90, v91
	v_mov_b32_e32 v94, v92
	v_mov_b32_e32 v95, v116
	v_mfma_f32_32x32x16_bf16 v[64:79], v[164:167], v[80:83], v[64:79]
	v_mov_b32_e32 v116, v93
	v_add_f32_e64 v84, v94, v116
	v_add_f32_e64 v85, v95, v117
	v_add_f32_e64 v194, v194, v84
	v_add_f32_e64 v195, v195, v85
	v_mfma_f32_32x32x16_bf16 v[16:31], v[160:163], v[80:83], v[16:31]
	s_cbranch_scc0 .LBB0_82
	s_lshl_b32 s4, s35, 14
	s_add_i32 s5, s4, 32
	v_add_u32_e32 v92, s5, v217
	v_add_u32_e32 v180, v92, v219
	v_add_u32_e32 v196, v92, v218
	v_add_u32_e32 v197, v92, v216
	v_add_u32_e32 v198, v92, v215
	s_waitcnt vmcnt(4)
	s_barrier
	ds_read_b128 v[80:83], v180
	ds_read_b128 v[84:87], v180 offset:4096
	ds_read_b128 v[160:163], v196
	ds_read_b128 v[164:167], v196 offset:4096
	ds_read_b128 v[88:91], v197
	ds_read_b128 v[168:171], v197 offset:4096
	ds_read_b128 v[172:175], v198
	ds_read_b128 v[176:179], v198 offset:4096
	s_waitcnt lgkmcnt(0)
	v_mfma_f32_32x32x16_bf16 v[128:143], v[80:83], v[152:155], v[0:15]
	v_mfma_f32_32x32x16_bf16 v[96:111], v[88:91], v[156:159], v[0:15]
	v_mfma_f32_32x32x16_bf16 v[112:127], v[84:87], v[152:155], v[0:15]
	v_mfma_f32_32x32x16_bf16 v[80:95], v[168:171], v[156:159], v[0:15]
	v_mfma_f32_32x32x16_bf16 v[128:143], v[160:163], v[144:147], v[128:143]
	v_mfma_f32_32x32x16_bf16 v[96:111], v[172:175], v[148:151], v[96:111]
	v_mfma_f32_32x32x16_bf16 v[112:127], v[164:167], v[144:147], v[112:127]
	v_mfma_f32_32x32x16_bf16 v[80:95], v[176:179], v[148:151], v[80:95]
	ds_read_b128 v[188:191], v180 offset:8192
	ds_read_b128 v[184:187], v180 offset:12288
	ds_read_b128 v[180:183], v196 offset:8192
	ds_read_b128 v[176:179], v196 offset:12288
	ds_read_b128 v[172:175], v197 offset:8192
	ds_read_b128 v[168:171], v197 offset:12288
	ds_read_b128 v[164:167], v198 offset:8192
	ds_read_b128 v[160:163], v198 offset:12288
	s_nop 0
	v_exp_f32_e32 v128, v128
	v_exp_f32_e32 v129, v129
	v_exp_f32_e32 v130, v130
	v_exp_f32_e32 v131, v131
	v_exp_f32_e32 v132, v132
	v_exp_f32_e32 v133, v133
	v_exp_f32_e32 v134, v134
	v_exp_f32_e32 v135, v135
	v_add_f32_e64 v196, v128, 0
	v_add_f32_e64 v197, v129, 0
	v_cvt_pk_bf16_f32 v128, v128, v129
	v_add_f32_e64 v196, v130, v196
	v_add_f32_e64 v197, v131, v197
	v_cvt_pk_bf16_f32 v129, v130, v131
	v_cvt_pk_bf16_f32 v130, v132, v133
	v_cvt_pk_bf16_f32 v131, v134, v135
	v_add_f32_e64 v196, v132, v196
	v_add_f32_e64 v197, v133, v197
	v_exp_f32_e32 v136, v136
	s_waitcnt lgkmcnt(0)
; DI void softmax_tile(f32x16 (&S)[2], float& lsum) {
;     f2_t ps = {0.f, 0.f};
; #pragma unroll
;     for (int t = 0; t < 2; ++t)
; #pragma unroll
;         for (int e = 0; e < 16; e += 2) {
;             f2_t pv; pv.x = __builtin_amdgcn_exp2f(S[t][e]); pv.y = __builtin_amdgcn_exp2f(S[t][e + 1]);
;             S[t][e] = pv.x; S[t][e + 1] = pv.y;
;             ps += pv;
;         }
;     lsum += ps.x + ps.y;
; }
; DI void pv_tile(const f32x16 (&S)[2], f32x16 (&O)[2], const bf16x8 (&vf)[8]) {
; #pragma unroll
;     for (int s = 0; s < 4; ++s) {
;         const bf16x8 pf = pack8(S[s >> 1], s & 1);
; template <int KIND>
; DI void attn_unit(const Params& p, int l, int b, int head, int qt, int qcol, int kcol, int vfeat, int gcol, int mixcol,
;                   int t1, int n1, int t2, int n2, char* smem) {
;     ...
;     for (int it = 0; it < nt; ++it) {
;         const int tile = (it < n1) ? t1 + it : t2 + (it - n1);
;         if (it + 1 < nt) asm volatile("s_waitcnt vmcnt(4)" ::: "memory"); else asm volatile("s_waitcnt vmcnt(0)" ::: "memory");
;         __builtin_amdgcn_s_barrier();
;         const char* sk = smem + sc * ATT_SLOT;
;         const char* sv = sk + ATT_V;
;         bool active = true;
;         if (KIND == 2 && tile < 32) active = (tile >= r0w) && (tile < r0w + 8);
;         bf16x8 kf[8], vf[8];
;         if (active) {
; #pragma unroll
;             for (int s = 0; s < 4; ++s)
; #pragma unroll
;                 for (int t = 0; t < 2; ++t) kf[2 * s + t] = *(const bf16x8*)(sk + (32 * t + r) * 128 + (((2 * s + h) ^ xr) << 4));
;         }
;         __builtin_amdgcn_sched_barrier(0);
;         if (it + 2 < nt) { const int nx = (it + 2 < n1) ? t1 + it + 2 : t2 + (it + 2 - n1); KV_ISSUE(nx, sn); }
;         sc = (sc == 2) ? 0 : sc + 1; sn = (sn == 2) ? 0 : sn + 1;
;         __builtin_amdgcn_sched_barrier(0);
;         if (active) {
;     ...
;             if (KIND == 0) {
;                 f32x16 S0[2], S1[2];
; #pragma unroll
;                 for (int t = 0; t < 2; ++t) { S0[t] = MFMA(kf[t], qf[0], cz); S1[t] = MFMA(kf[4 + t], qf[2], cz); }
; #pragma unroll
;                 for (int t = 0; t < 2; ++t) { S0[t] = MFMA(kf[2 + t], qf[1], S0[t]); S1[t] = MFMA(kf[6 + t], qf[3], S1[t]); }
;                 LOAD_VF();
;                 softmax_tile(S0, l0);
;                 pv_tile(S0, O0, vf);
;                 softmax_tile(S1, l1);
;                 pv_tile(S1, O1, vf);
	v_mfma_f32_32x32x16_bf16 v[48:63], v[188:191], v[128:131], v[48:63]
	v_exp_f32_e32 v137, v137
	v_exp_f32_e32 v138, v138
	v_exp_f32_e32 v139, v139
	v_exp_f32_e32 v132, v140
	v_exp_f32_e32 v133, v141
	v_exp_f32_e32 v140, v142
	v_exp_f32_e32 v141, v143
	v_mfma_f32_32x32x16_bf16 v[32:47], v[184:187], v[128:131], v[32:47]
	v_add_f32_e64 v134, v134, v196
	v_add_f32_e64 v135, v135, v197
	v_cvt_pk_bf16_f32 v128, v136, v137
	v_cvt_pk_bf16_f32 v129, v138, v139
	v_cvt_pk_bf16_f32 v130, v132, v133
	v_cvt_pk_bf16_f32 v131, v140, v141
	v_add_f32_e64 v134, v136, v134
	v_add_f32_e64 v135, v137, v135
	v_exp_f32_e32 v112, v112
	v_mfma_f32_32x32x16_bf16 v[48:63], v[180:183], v[128:131], v[48:63]
	v_add_f32_e64 v134, v138, v134
	v_add_f32_e64 v135, v139, v135
	v_exp_f32_e32 v113, v113
	v_add_f32_e64 v134, v132, v134
	v_add_f32_e64 v135, v133, v135
	v_exp_f32_e32 v116, v116
	v_add_f32_e64 v132, v140, v134
	v_add_f32_e64 v133, v141, v135
	v_exp_f32_e32 v134, v114
	v_exp_f32_e32 v135, v115
	v_mfma_f32_32x32x16_bf16 v[32:47], v[176:179], v[128:131], v[32:47]
	v_exp_f32_e32 v117, v117
	v_exp_f32_e32 v118, v118
	v_exp_f32_e32 v119, v119
	v_add_f32_e64 v132, v112, v132
	v_add_f32_e64 v133, v113, v133
	v_cvt_pk_bf16_f32 v112, v112, v113
	v_cvt_pk_bf16_f32 v113, v134, v135
	v_cvt_pk_bf16_f32 v114, v116, v117
	v_cvt_pk_bf16_f32 v115, v118, v119
	v_add_f32_e64 v128, v134, v132
	v_add_f32_e64 v129, v135, v133
	v_exp_f32_e32 v120, v120
	v_mfma_f32_32x32x16_bf16 v[48:63], v[172:175], v[112:115], v[48:63]
	v_add_f32_e64 v116, v116, v128
	v_add_f32_e64 v117, v117, v129
	v_exp_f32_e32 v121, v121
	v_add_f32_e64 v116, v118, v116
	v_add_f32_e64 v117, v119, v117
	v_exp_f32_e32 v118, v122
	v_exp_f32_e32 v119, v123
	v_exp_f32_e32 v122, v124
	v_exp_f32_e32 v123, v125
	v_mfma_f32_32x32x16_bf16 v[32:47], v[168:171], v[112:115], v[32:47]
	v_exp_f32_e32 v124, v126
	v_exp_f32_e32 v125, v127
	v_exp_f32_e32 v96, v96
	v_exp_f32_e32 v97, v97
	v_exp_f32_e32 v98, v98
	v_exp_f32_e32 v99, v99
	v_exp_f32_e32 v100, v100
	v_exp_f32_e32 v101, v101
	v_exp_f32_e32 v102, v102
	v_exp_f32_e32 v103, v103
	v_cvt_pk_bf16_f32 v112, v120, v121
	v_cvt_pk_bf16_f32 v113, v118, v119
	v_cvt_pk_bf16_f32 v114, v122, v123
	v_cvt_pk_bf16_f32 v115, v124, v125
	v_exp_f32_e32 v104, v104
	v_exp_f32_e32 v105, v105
	v_mfma_f32_32x32x16_bf16 v[48:63], v[164:167], v[112:115], v[48:63]
	v_exp_f32_e32 v106, v106
	v_exp_f32_e32 v107, v107
	v_exp_f32_e32 v80, v80
	v_exp_f32_e32 v81, v81
	v_exp_f32_e32 v82, v82
	v_exp_f32_e32 v83, v83
	v_exp_f32_e32 v84, v84
	v_mfma_f32_32x32x16_bf16 v[32:47], v[160:163], v[112:115], v[32:47]
	v_add_f32_e64 v112, v96, 0
	v_add_f32_e64 v113, v97, 0
	v_cvt_pk_bf16_f32 v96, v96, v97
	v_add_f32_e64 v112, v98, v112
	v_add_f32_e64 v113, v99, v113
	v_cvt_pk_bf16_f32 v97, v98, v99
	v_cvt_pk_bf16_f32 v98, v100, v101
	v_cvt_pk_bf16_f32 v99, v102, v103
	v_add_f32_e64 v112, v100, v112
	v_add_f32_e64 v113, v101, v113
	v_exp_f32_e32 v100, v108
	v_mfma_f32_32x32x16_bf16 v[64:79], v[188:191], v[96:99], v[64:79]
	v_exp_f32_e32 v101, v109
	v_add_f32_e64 v112, v102, v112
	v_add_f32_e64 v113, v103, v113
	v_exp_f32_e32 v102, v110
	v_exp_f32_e32 v103, v111
	v_add_f32_e64 v112, v104, v112
	v_add_f32_e64 v113, v105, v113
	v_exp_f32_e32 v85, v85
	v_add_f32_e64 v112, v106, v112
	v_add_f32_e64 v113, v107, v113
	v_mfma_f32_32x32x16_bf16 v[16:31], v[184:187], v[96:99], v[16:31]
	v_add_f32_e64 v108, v100, v112
	v_add_f32_e64 v109, v101, v113
	v_cvt_pk_bf16_f32 v98, v100, v101
	v_add_f32_e64 v96, v102, v108
	v_add_f32_e64 v97, v103, v109
	v_cvt_pk_bf16_f32 v99, v102, v103
	v_add_f32_e64 v108, v80, v96
	v_add_f32_e64 v109, v81, v97
	v_cvt_pk_bf16_f32 v96, v104, v105
	v_cvt_pk_bf16_f32 v97, v106, v107
	v_exp_f32_e32 v86, v86
	v_exp_f32_e32 v87, v87
	v_mfma_f32_32x32x16_bf16 v[64:79], v[180:183], v[96:99], v[64:79]
	v_add_f32_e64 v100, v82, v108
	v_add_f32_e64 v101, v83, v109
	v_exp_f32_e32 v88, v88
	v_add_f32_e64 v100, v84, v100
	v_add_f32_e64 v101, v85, v101
	v_exp_f32_e32 v89, v89
	v_cvt_pk_bf16_f32 v80, v80, v81
	v_cvt_pk_bf16_f32 v81, v82, v83
	v_cvt_pk_bf16_f32 v82, v84, v85
	v_mfma_f32_32x32x16_bf16 v[16:31], v[176:179], v[96:99], v[16:31]
	v_cvt_pk_bf16_f32 v83, v86, v87
	v_add_f32_e64 v96, v86, v100
	v_add_f32_e64 v97, v87, v101
	v_exp_f32_e32 v86, v90
	v_exp_f32_e32 v87, v91
	v_exp_f32_e32 v90, v92
	v_exp_f32_e32 v91, v93
	v_exp_f32_e32 v92, v94
	v_mfma_f32_32x32x16_bf16 v[64:79], v[172:175], v[80:83], v[64:79]
	v_exp_f32_e32 v93, v95
	s_addk_i32 s4, 0x4000
	v_add_f32_e64 v84, v88, v96
	v_add_f32_e64 v85, v89, v97
	s_cmp_lg_u32 s35, 2
	s_cselect_b32 s4, s4, 0
	s_add_i32 s4, s4, 32
	s_waitcnt vmcnt(0)
	v_mfma_f32_32x32x16_bf16 v[16:31], v[168:171], v[80:83], v[16:31]
	v_add_f32_e64 v80, v86, v84
	v_add_f32_e64 v81, v87, v85
	v_cvt_pk_bf16_f32 v82, v90, v91
	v_add_f32_e64 v80, v90, v80
	v_add_f32_e64 v81, v91, v81
	v_cvt_pk_bf16_f32 v83, v92, v93
	v_add_f32_e64 v168, v92, v80
	v_add_f32_e64 v169, v93, v81
	v_cvt_pk_bf16_f32 v80, v88, v89
	v_add_u32_e32 v88, s4, v217
	v_cvt_pk_bf16_f32 v81, v86, v87
	v_add_u32_e32 v174, v88, v219
	v_add_u32_e32 v175, v88, v218
	v_add_u32_e32 v176, v88, v216
	v_add_u32_e32 v177, v88, v215
	v_mfma_f32_32x32x16_bf16 v[64:79], v[164:167], v[80:83], v[64:79]
	s_barrier
; #define MFMA(a, b, c) __builtin_amdgcn_mfma_f32_32x32x16_bf16((a), (b), (c), 0, 0, 0)
; template <int KIND>
; DI void attn_unit(const Params& p, int l, int b, int head, int qt, int qcol, int kcol, int vfeat, int gcol, int mixcol,
;                   int t1, int n1, int t2, int n2, char* smem) {
;     ...
;     for (int it = 0; it < nt; ++it) {
;         const int tile = (it < n1) ? t1 + it : t2 + (it - n1);
;         if (it + 1 < nt) asm volatile("s_waitcnt vmcnt(4)" ::: "memory"); else asm volatile("s_waitcnt vmcnt(0)" ::: "memory");
;         __builtin_amdgcn_s_barrier();
;         const char* sk = smem + sc * ATT_SLOT;
;         const char* sv = sk + ATT_V;
;         bool active = true;
;         if (KIND == 2 && tile < 32) active = (tile >= r0w) && (tile < r0w + 8);
;         bf16x8 kf[8], vf[8];
;         if (active) {
; #pragma unroll
;             for (int s = 0; s < 4; ++s)
; #pragma unroll
;                 for (int t = 0; t < 2; ++t) kf[2 * s + t] = *(const bf16x8*)(sk + (32 * t + r) * 128 + (((2 * s + h) ^ xr) << 4));
;         }
;         __builtin_amdgcn_sched_barrier(0);
;         if (it + 2 < nt) { const int nx = (it + 2 < n1) ? t1 + it + 2 : t2 + (it + 2 - n1); KV_ISSUE(nx, sn); }
;         sc = (sc == 2) ? 0 : sc + 1; sn = (sn == 2) ? 0 : sn + 1;
;         __builtin_amdgcn_sched_barrier(0);
;         if (active) {
;     ...
;             if (KIND == 0) {
;                 f32x16 S0[2], S1[2];
; #pragma unroll
;                 for (int t = 0; t < 2; ++t) { S0[t] = MFMA(kf[t], qf[0], cz); S1[t] = MFMA(kf[4 + t], qf[2], cz); }
; #pragma unroll
;                 for (int t = 0; t < 2; ++t) { S0[t] = MFMA(kf[2 + t], qf[1], S0[t]); S1[t] = MFMA(kf[6 + t], qf[3], S1[t]); }
;                 LOAD_VF();
;                 softmax_tile(S0, l0);
;                 pv_tile(S0, O0, vf);
;                 softmax_tile(S1, l1);
;                 pv_tile(S1, O1, vf);
;     ...
;     l0 = xsum32(l0);
;     const float inv0 = 1.f / l0;
;     const int tid_e = otid();
;     const size_t qrow_e = (size_t)b * TPB + qt * 128 + 32 * (tid_e >> 6) + (tid_e & 31);
;     bf16_t* orow = p.hmix + ((size_t)(mixcol >> 5) * NTOK + qrow_e) * 32;
;     const bf16_t* grow = p.qkv + ((size_t)(gcol >> 6) * NTOK + qrow_e) * 64;
;     if (KIND == 0) {
;         l1 = xsum32(l1);
;         const float lam = p.lam[l];
;         const float inv1 = lam / l1;
	ds_read_b128 v[84:87], v174
	ds_read_b128 v[128:131], v174 offset:4096
	ds_read_b128 v[132:135], v175
	ds_read_b128 v[136:139], v175 offset:4096
	ds_read_b128 v[96:99], v176
	ds_read_b128 v[140:143], v176 offset:4096
	ds_read_b128 v[164:167], v177
	ds_read_b128 v[170:173], v177 offset:4096
	v_add_f32_e64 v116, v120, v116
	v_add_f32_e64 v117, v121, v117
	s_nop 0
	v_add_f32_e64 v116, v118, v116
	v_add_f32_e64 v117, v119, v117
	v_mfma_f32_32x32x16_bf16 v[16:31], v[160:163], v[80:83], v[16:31]
	v_add_f32_e64 v116, v122, v116
	v_add_f32_e64 v117, v123, v117
	v_add_f32_e64 v196, v124, v116
	v_add_f32_e64 v197, v125, v117
	s_waitcnt lgkmcnt(0)
	v_mfma_f32_32x32x16_bf16 v[112:127], v[84:87], v[152:155], v[0:15]
	v_mfma_f32_32x32x16_bf16 v[80:95], v[96:99], v[156:159], v[0:15]
	v_mfma_f32_32x32x16_bf16 v[96:111], v[128:131], v[152:155], v[0:15]
	v_mfma_f32_32x32x16_bf16 v[0:15], v[140:143], v[156:159], v[0:15]
	v_mfma_f32_32x32x16_bf16 v[112:127], v[132:135], v[144:147], v[112:127]
	v_mfma_f32_32x32x16_bf16 v[80:95], v[164:167], v[148:151], v[80:95]
	v_mfma_f32_32x32x16_bf16 v[96:111], v[136:139], v[144:147], v[96:111]
	v_mfma_f32_32x32x16_bf16 v[0:15], v[170:173], v[148:151], v[0:15]
	ds_read_b128 v[156:159], v174 offset:8192
	ds_read_b128 v[152:155], v174 offset:12288
	ds_read_b128 v[148:151], v175 offset:8192
	ds_read_b128 v[144:147], v175 offset:12288
	ds_read_b128 v[140:143], v176 offset:8192
	ds_read_b128 v[136:139], v176 offset:12288
	ds_read_b128 v[132:135], v177 offset:8192
	ds_read_b128 v[128:131], v177 offset:12288
	s_nop 0
	v_exp_f32_e32 v112, v112
	v_exp_f32_e32 v113, v113
	v_exp_f32_e32 v114, v114
	v_exp_f32_e32 v115, v115
	v_exp_f32_e32 v116, v116
	v_exp_f32_e32 v117, v117
	v_exp_f32_e32 v118, v118
	v_exp_f32_e32 v119, v119
	v_add_f32_e64 v160, v112, 0
	v_add_f32_e64 v161, v113, 0
	v_cvt_pk_bf16_f32 v112, v112, v113
	v_add_f32_e64 v160, v114, v160
	v_add_f32_e64 v161, v115, v161
	v_cvt_pk_bf16_f32 v113, v114, v115
	v_cvt_pk_bf16_f32 v114, v116, v117
	v_cvt_pk_bf16_f32 v115, v118, v119
	v_exp_f32_e32 v120, v120
	v_exp_f32_e32 v121, v121
	s_waitcnt lgkmcnt(0)
	v_mfma_f32_32x32x16_bf16 v[48:63], v[156:159], v[112:115], v[48:63]
	v_exp_f32_e32 v122, v122
	v_exp_f32_e32 v123, v123
	v_exp_f32_e32 v124, v124
	v_exp_f32_e32 v125, v125
	v_exp_f32_e32 v126, v126
	v_exp_f32_e32 v127, v127
	v_add_f32_e64 v160, v116, v160
	v_add_f32_e64 v161, v117, v161
	v_mfma_f32_32x32x16_bf16 v[32:47], v[152:155], v[112:115], v[32:47]
	v_add_f32_e64 v160, v118, v160
	v_add_f32_e64 v161, v119, v161
	v_exp_f32_e32 v118, v96
	v_add_f32_e64 v160, v120, v160
	v_add_f32_e64 v161, v121, v161
	v_exp_f32_e32 v119, v97
	v_add_f32_e64 v116, v122, v160
	v_add_f32_e64 v117, v123, v161
	v_exp_f32_e32 v160, v98
	v_exp_f32_e32 v161, v99
	v_cvt_pk_bf16_f32 v96, v120, v121
	v_cvt_pk_bf16_f32 v97, v122, v123
	v_cvt_pk_bf16_f32 v98, v124, v125
	v_cvt_pk_bf16_f32 v99, v126, v127
	v_add_f32_e64 v116, v124, v116
	v_add_f32_e64 v117, v125, v117
	v_exp_f32_e32 v100, v100
	v_mfma_f32_32x32x16_bf16 v[48:63], v[148:151], v[96:99], v[48:63]
	v_exp_f32_e32 v101, v101
	v_add_f32_e64 v116, v126, v116
	v_add_f32_e64 v117, v127, v117
	v_exp_f32_e32 v102, v102
	v_exp_f32_e32 v103, v103
	v_add_f32_e64 v112, v118, v116
	v_add_f32_e64 v113, v119, v117
	v_exp_f32_e32 v104, v104
	v_exp_f32_e32 v105, v105
	v_mfma_f32_32x32x16_bf16 v[32:47], v[144:147], v[96:99], v[32:47]
	v_add_f32_e64 v112, v160, v112
	v_add_f32_e64 v113, v161, v113
	v_exp_f32_e32 v106, v106
	v_exp_f32_e32 v107, v107
	v_add_f32_e64 v112, v100, v112
	v_add_f32_e64 v113, v101, v113
	v_exp_f32_e32 v108, v108
	v_add_f32_e64 v112, v102, v112
	v_add_f32_e64 v113, v103, v113
	v_cvt_pk_bf16_f32 v96, v118, v119
	v_cvt_pk_bf16_f32 v97, v160, v161
	v_cvt_pk_bf16_f32 v98, v100, v101
	v_cvt_pk_bf16_f32 v99, v102, v103
	v_exp_f32_e32 v109, v109
	v_exp_f32_e32 v100, v110
	v_mfma_f32_32x32x16_bf16 v[48:63], v[140:143], v[96:99], v[48:63]
	v_exp_f32_e32 v101, v111
	v_add_f32_e64 v102, v104, v112
	v_add_f32_e64 v103, v105, v113
	v_exp_f32_e32 v84, v84
	v_add_f32_e64 v102, v106, v102
	v_add_f32_e64 v103, v107, v103
	v_exp_f32_e32 v85, v85
	v_add_f32_e64 v102, v108, v102
	v_add_f32_e64 v103, v109, v103
	v_exp_f32_e32 v86, v86
	v_mfma_f32_32x32x16_bf16 v[32:47], v[136:139], v[96:99], v[32:47]
	v_cvt_pk_bf16_f32 v96, v104, v105
	v_exp_f32_e32 v104, v80
	v_exp_f32_e32 v105, v81
	v_cvt_pk_bf16_f32 v97, v106, v107
	v_exp_f32_e32 v106, v82
	v_exp_f32_e32 v107, v83
	v_exp_f32_e32 v87, v87
	v_add_f32_e64 v102, v100, v102
	v_add_f32_e64 v103, v101, v103
	v_add_f32_e64 v82, v104, 0
	v_add_f32_e64 v83, v105, 0
	v_exp_f32_e32 v88, v88
	v_exp_f32_e32 v89, v89
	v_mov_b32_e32 v110, v196
	v_mov_b32_e32 v111, v102
	v_mov_b32_e32 v102, v197
	v_add_f32_e64 v82, v106, v82
	v_add_f32_e64 v83, v107, v83
	v_exp_f32_e32 v90, v90
	v_exp_f32_e32 v91, v91
	v_cvt_pk_bf16_f32 v99, v100, v101
	v_add_f32_e64 v100, v110, v102
	v_add_f32_e64 v101, v111, v103
	v_add_f32_e64 v82, v84, v82
	v_add_f32_e64 v83, v85, v83
	v_exp_f32_e32 v92, v92
	v_exp_f32_e32 v93, v93
	s_add_u32 s7, s29, s7
	v_pk_add_f32 v[102:103], v[194:195], v[100:101] op_sel:[1,0] op_sel_hi:[0,1]
	v_add_f32_e64 v82, v86, v82
	v_add_f32_e64 v83, v87, v83
	s_addc_u32 s9, s9, 0
	s_add_i32 s8, s8, 0x36000
	s_lshl_b64 s[4:5], s[60:61], 2
	v_cvt_pk_bf16_f32 v98, v108, v109
	v_pk_add_f32 v[80:81], v[102:103], v[100:101] op_sel:[0,1] op_sel_hi:[1,0]
	v_add_f32_e64 v82, v88, v82
	v_add_f32_e64 v83, v89, v83
	s_add_u32 s4, s50, s4
	v_mfma_f32_32x32x16_bf16 v[48:63], v[132:135], v[96:99], v[48:63]
	v_mov_b32_e32 v81, v200
	s_addc_u32 s5, s51, s5
	v_cvt_pk_bf16_f32 v84, v84, v85
	v_cvt_pk_bf16_f32 v85, v86, v87
	v_exp_f32_e32 v94, v94
; DI float bf2f(bf16_t v) { return __uint_as_float(((unsigned)v) << 16); }
; DI int otid() { int t = threadIdx.x; asm volatile("" : "+v"(t)); return t; }
; DI float xsum32(float x) { const unsigned u = __float_as_uint(x); const auto r2 = __builtin_amdgcn_permlane32_swap(u, u, false, false); return __uint_as_float(r2[0]) + __uint_as_float(r2[1]); }
; template <int KIND>
; DI void attn_unit(const Params& p, int l, int b, int head, int qt, int qcol, int kcol, int vfeat, int gcol, int mixcol,
;                   int t1, int n1, int t2, int n2, char* smem) {
;     ...
;     l0 = xsum32(l0);
;     const float inv0 = 1.f / l0;
;     const int tid_e = otid();
;     const size_t qrow_e = (size_t)b * TPB + qt * 128 + 32 * (tid_e >> 6) + (tid_e & 31);
;     bf16_t* orow = p.hmix + ((size_t)(mixcol >> 5) * NTOK + qrow_e) * 32;
;     const bf16_t* grow = p.qkv + ((size_t)(gcol >> 6) * NTOK + qrow_e) * 64;
;     if (KIND == 0) {
;         l1 = xsum32(l1);
;         const float lam = p.lam[l];
;         const float inv1 = lam / l1;
;         float ss = 0.f;
; #pragma unroll
;         for (int t = 0; t < 2; ++t)
; #pragma unroll
;             for (int e = 0; e < 16; ++e) { const float o = O0[t][e] * inv0 - O1[t][e] * inv1; O0[t][e] = o; ss += o * o; }
;         ss = xsum32(ss);
;         const float rstd = rsqrtf(ss * (1.f / 64.f) + EPS) * p.lam[4 + l];
;         const float* sw = p.subln + l * 64;
; #pragma unroll
;         for (int t = 0; t < 2; ++t)
; #pragma unroll
;             for (int q = 0; q < 4; ++q) {
;                 const int f = 32 * t + 8 * q + 4 * h;
;                 const float4 w4 = *(const float4*)(sw + f);
;                 const uint2 gg = *(const uint2*)(grow + f);
;                 const float g0 = bf2f((bf16_t)(gg.x & 0xffff)), g1 = bf2f((bf16_t)(gg.x >> 16)), g2 = bf2f((bf16_t)(gg.y & 0xffff)), g3 = bf2f((bf16_t)(gg.y >> 16));
	v_exp_f32_e32 v95, v95
	v_mfma_f32_32x32x16_bf16 v[32:47], v[128:131], v[96:99], v[32:47]
	v_add_f32_e64 v96, v90, v82
	v_add_f32_e64 v97, v91, v83
	v_exp_f32_e32 v98, v0
	v_exp_f32_e32 v99, v1
	v_add_f32_e64 v0, v92, v96
	v_add_f32_e64 v1, v93, v97
	global_load_dword v96, v193, s[4:5]
	v_cvt_pk_bf16_f32 v82, v104, v105
	v_cvt_pk_bf16_f32 v83, v106, v107
	v_exp_f32_e32 v100, v2
	v_exp_f32_e32 v101, v3
	v_mfma_f32_32x32x16_bf16 v[64:79], v[156:159], v[82:85], v[64:79]
	v_exp_f32_e32 v86, v4
	v_exp_f32_e32 v87, v5
	v_cvt_pk_bf16_f32 v2, v88, v89
	v_cvt_pk_bf16_f32 v3, v90, v91
	v_cvt_pk_bf16_f32 v4, v92, v93
	v_cvt_pk_bf16_f32 v5, v94, v95
	v_add_f32_e64 v0, v94, v0
	v_add_f32_e64 v1, v95, v1
	v_mfma_f32_32x32x16_bf16 v[16:31], v[152:155], v[82:85], v[16:31]
	v_exp_f32_e32 v6, v6
	v_exp_f32_e32 v7, v7
	v_add_f32_e64 v0, v98, v0
	v_add_f32_e64 v1, v99, v1
	v_exp_f32_e32 v8, v8
	v_exp_f32_e32 v9, v9
	v_add_f32_e64 v0, v100, v0
	v_add_f32_e64 v1, v101, v1
	v_exp_f32_e32 v10, v10
	v_mfma_f32_32x32x16_bf16 v[64:79], v[148:151], v[2:5], v[64:79]
	v_exp_f32_e32 v11, v11
	v_add_f32_e64 v82, v86, v0
	v_add_f32_e64 v83, v87, v1
	v_exp_f32_e32 v12, v12
	v_exp_f32_e32 v13, v13
	v_add_f32_e64 v82, v6, v82
	v_add_f32_e64 v83, v7, v83
	v_ashrrev_i32_e32 v0, 1, v81
	v_and_b32_e32 v0, 0xffffffe0, v0
	v_mfma_f32_32x32x16_bf16 v[16:31], v[144:147], v[2:5], v[16:31]
	v_cvt_pk_bf16_f32 v5, v6, v7
	v_exp_f32_e32 v6, v14
	v_exp_f32_e32 v7, v15
	v_add_f32_e64 v14, v8, v82
	v_add_f32_e64 v15, v9, v83
	v_cvt_pk_bf16_f32 v2, v98, v99
	v_add_f32_e64 v14, v10, v14
	v_add_f32_e64 v15, v11, v15
	v_cvt_pk_bf16_f32 v3, v100, v101
	v_cvt_pk_bf16_f32 v4, v86, v87
	v_add_f32_e64 v14, v12, v14
	v_add_f32_e64 v15, v13, v15
	v_ashrrev_i32_e32 v1, 31, v0
	v_mfma_f32_32x32x16_bf16 v[64:79], v[140:143], v[2:5], v[64:79]
	v_add_f32_e64 v14, v6, v14
	v_add_f32_e64 v15, v7, v15
	v_and_or_b32 v84, v81, 31, s7
	v_mov_b32_e32 v85, s9
	v_lshl_add_u64 v[84:85], v[84:85], 0, v[0:1]
	s_mov_b32 s9, s75
	v_lshl_add_u64 v[0:1], v[84:85], 0, s[8:9]
	v_mov_b32_e32 v82, v168
	v_mfma_f32_32x32x16_bf16 v[16:31], v[136:139], v[2:5], v[16:31]
	v_cvt_pk_bf16_f32 v5, v6, v7
	v_mov_b32_e32 v6, v80
	s_nop 1
	v_permlane32_swap_b32_e32 v80, v6
	v_cvt_pk_bf16_f32 v2, v8, v9
	v_add_f32_e32 v8, v80, v6
	v_div_scale_f32 v9, s[8:9], v8, v8, 1.0
	v_cvt_pk_bf16_f32 v3, v10, v11
	v_rcp_f32_e32 v10, v9
	v_cvt_pk_bf16_f32 v4, v12, v13
	v_mov_b32_e32 v83, v14
	v_mov_b32_e32 v14, v169
	v_mfma_f32_32x32x16_bf16 v[64:79], v[132:135], v[2:5], v[64:79]
	v_add_f32_e64 v14, v82, v14
	v_add_f32_e64 v15, v83, v15
	global_load_dword v80, v193, s[4:5] offset:16
	v_add_f32_e64 v6, v194, v14
	v_add_f32_e64 v7, v195, v15
	v_lshlrev_b64 v[0:1], 7, v[0:1]
	v_pk_add_f32 v[6:7], v[6:7], v[14:15] op_sel:[0,1] op_sel_hi:[1,0]
	v_lshl_add_u64 v[0:1], s[40:41], 0, v[0:1]
	v_lshlrev_b32_e32 v88, 3, v214
	v_mfma_f32_32x32x16_bf16 v[16:31], v[128:131], v[2:5], v[16:31]
	v_fma_f32 v2, -v9, v10, 1.0
	v_fmac_f32_e32 v10, v2, v10
	v_div_scale_f32 v2, vcc, 1.0, v8, 1.0
	v_mul_f32_e32 v3, v2, v10
	v_fma_f32 v4, -v9, v3, v2
	v_fmac_f32_e32 v3, v4, v10
	v_fma_f32 v2, -v9, v3, v2
	v_div_fmas_f32 v2, v2, v10, v3
	v_div_fixup_f32 v8, v2, v8, 1.0
	v_mov_b32_e32 v2, v6
	s_nop 1
	v_permlane32_swap_b32_e32 v6, v2
	v_add_f32_e32 v4, v6, v2
	s_waitcnt vmcnt(0)
	v_div_scale_f32 v5, s[4:5], v4, v4, v96
	v_rcp_f32_e32 v6, v5
	v_mov_b32_e32 v89, v193
	v_lshl_add_u64 v[0:1], v[0:1], 0, v[88:89]
	s_mul_i32 s6, s6, 0x9000
	v_fma_f32 v7, -v5, v6, 1.0
	s_mov_b32 s7, s75
	v_fmac_f32_e32 v6, v7, v6
	v_div_scale_f32 v7, vcc, v96, v4, v96
	global_load_dwordx2 v[90:91], v[0:1], off
	v_lshl_add_u64 v[2:3], v[84:85], 0, s[6:7]
	v_mul_f32_e32 v9, v7, v6
	s_load_dwordx2 s[4:5], s[0:1], 0xb8
	s_load_dwordx2 s[6:7], s[0:1], 0x78
	v_fma_f32 v10, -v5, v9, v7
	v_fmac_f32_e32 v9, v10, v6
	v_fma_f32 v5, -v5, v9, v7
	v_lshlrev_b64 v[2:3], 6, v[2:3]
	v_div_fmas_f32 v5, v5, v6, v9
	v_div_fixup_f32 v10, v5, v4, v96
	s_waitcnt lgkmcnt(0)
	v_lshl_add_u64 v[2:3], s[4:5], 0, v[2:3]
	s_add_u32 s4, s6, s46
	s_addc_u32 s5, s7, s47
	v_pk_mul_f32 v[4:5], v[66:67], v[10:11] op_sel_hi:[1,0]
	v_pk_mul_f32 v[16:17], v[16:17], v[10:11] op_sel_hi:[1,0]
	v_pk_fma_f32 v[14:15], v[50:51], v[8:9], v[4:5] op_sel_hi:[1,0,1] neg_lo:[0,0,1] neg_hi:[0,0,1]
	global_load_dwordx4 v[4:7], v192, s[4:5]
	v_pk_mul_f32 v[50:51], v[64:65], v[10:11] op_sel_hi:[1,0]
	v_mul_f32_e32 v64, v15, v15
	v_pk_fma_f32 v[48:49], v[48:49], v[8:9], v[50:51] op_sel_hi:[1,0,1] neg_lo:[0,0,1] neg_hi:[0,0,1]
	v_pk_mul_f32 v[18:19], v[18:19], v[10:11] op_sel_hi:[1,0]
	v_mul_f32_e32 v50, v49, v49
	v_pk_fma_f32 v[50:51], v[48:49], v[48:49], v[50:51] op_sel_hi:[1,1,0]
	v_pk_fma_f32 v[16:17], v[32:33], v[8:9], v[16:17] op_sel_hi:[1,0,1] neg_lo:[0,0,1] neg_hi:[0,0,1]
	v_pk_fma_f32 v[50:51], v[14:15], v[14:15], v[50:51]
	v_pk_fma_f32 v[18:19], v[34:35], v[8:9], v[18:19] op_sel_hi:[1,0,1] neg_lo:[0,0,1] neg_hi:[0,0,1]
	v_pk_add_f32 v[50:51], v[64:65], v[50:51] op_sel_hi:[0,1]
	v_pk_mul_f32 v[64:65], v[70:71], v[10:11] op_sel_hi:[1,0]
	v_mul_f32_e32 v34, v17, v17
	v_pk_fma_f32 v[54:55], v[54:55], v[8:9], v[64:65] op_sel_hi:[1,0,1] neg_lo:[0,0,1] neg_hi:[0,0,1]
	v_pk_mul_f32 v[64:65], v[68:69], v[10:11] op_sel_hi:[1,0]
	v_pk_mul_f32 v[20:21], v[20:21], v[10:11] op_sel_hi:[1,0]
	v_pk_fma_f32 v[52:53], v[52:53], v[8:9], v[64:65] op_sel_hi:[1,0,1] neg_lo:[0,0,1] neg_hi:[0,0,1]
	v_pk_fma_f32 v[20:21], v[36:37], v[8:9], v[20:21] op_sel_hi:[1,0,1] neg_lo:[0,0,1] neg_hi:[0,0,1]
	v_pk_fma_f32 v[50:51], v[52:53], v[52:53], v[50:51]
	v_mul_f32_e32 v64, v53, v53
	v_pk_add_f32 v[50:51], v[64:65], v[50:51] op_sel_hi:[0,1]
	v_pk_fma_f32 v[50:51], v[54:55], v[54:55], v[50:51]
; DI unsigned pk2(float a, float b) { f2_t v = {a, b}; bf2_t r = __builtin_convertvector(v, bf2_t); return __builtin_bit_cast(unsigned, r); }
; DI float bf2f(bf16_t v) { return __uint_as_float(((unsigned)v) << 16); }
; DI float xsum32(float x) { const unsigned u = __float_as_uint(x); const auto r2 = __builtin_amdgcn_permlane32_swap(u, u, false, false); return __uint_as_float(r2[0]) + __uint_as_float(r2[1]); }
; template <int KIND>
; DI void attn_unit(const Params& p, int l, int b, int head, int qt, int qcol, int kcol, int vfeat, int gcol, int mixcol,
;                   int t1, int n1, int t2, int n2, char* smem) {
;     ...
;         float ss = 0.f;
; #pragma unroll
;         for (int t = 0; t < 2; ++t)
; #pragma unroll
;             for (int e = 0; e < 16; ++e) { const float o = O0[t][e] * inv0 - O1[t][e] * inv1; O0[t][e] = o; ss += o * o; }
;         ss = xsum32(ss);
;         const float rstd = rsqrtf(ss * (1.f / 64.f) + EPS) * p.lam[4 + l];
;         const float* sw = p.subln + l * 64;
; #pragma unroll
;         for (int t = 0; t < 2; ++t)
; #pragma unroll
;             for (int q = 0; q < 4; ++q) {
;                 const int f = 32 * t + 8 * q + 4 * h;
;                 const float4 w4 = *(const float4*)(sw + f);
;                 const uint2 gg = *(const uint2*)(grow + f);
;                 const float g0 = bf2f((bf16_t)(gg.x & 0xffff)), g1 = bf2f((bf16_t)(gg.x >> 16)), g2 = bf2f((bf16_t)(gg.y & 0xffff)), g3 = bf2f((bf16_t)(gg.y >> 16));
;                 uint2 o;
;                 o.x = pk2(O0[t][4 * q + 0] * rstd * w4.x * g0, O0[t][4 * q + 1] * rstd * w4.y * g1);
;                 o.y = pk2(O0[t][4 * q + 2] * rstd * w4.z * g2, O0[t][4 * q + 3] * rstd * w4.w * g3);
;                 *(uint2*)(orow + (size_t)t * NTOK * 32 + 8 * q + 4 * h) = o;
	v_mul_f32_e32 v64, v55, v55
	v_pk_add_f32 v[50:51], v[64:65], v[50:51] op_sel_hi:[0,1]
	v_pk_mul_f32 v[64:65], v[74:75], v[10:11] op_sel_hi:[1,0]
	v_pk_mul_f32 v[22:23], v[22:23], v[10:11] op_sel_hi:[1,0]
	v_pk_fma_f32 v[58:59], v[58:59], v[8:9], v[64:65] op_sel_hi:[1,0,1] neg_lo:[0,0,1] neg_hi:[0,0,1]
	v_pk_mul_f32 v[64:65], v[72:73], v[10:11] op_sel_hi:[1,0]
	v_pk_fma_f32 v[22:23], v[38:39], v[8:9], v[22:23] op_sel_hi:[1,0,1] neg_lo:[0,0,1] neg_hi:[0,0,1]
	v_pk_fma_f32 v[56:57], v[56:57], v[8:9], v[64:65] op_sel_hi:[1,0,1] neg_lo:[0,0,1] neg_hi:[0,0,1]
	v_pk_mul_f32 v[24:25], v[24:25], v[10:11] op_sel_hi:[1,0]
	v_pk_fma_f32 v[50:51], v[56:57], v[56:57], v[50:51]
	v_mul_f32_e32 v64, v57, v57
	v_pk_add_f32 v[50:51], v[64:65], v[50:51] op_sel_hi:[0,1]
	v_pk_fma_f32 v[50:51], v[58:59], v[58:59], v[50:51]
	v_mul_f32_e32 v64, v59, v59
	v_pk_add_f32 v[50:51], v[64:65], v[50:51] op_sel_hi:[0,1]
	v_pk_mul_f32 v[64:65], v[78:79], v[10:11] op_sel_hi:[1,0]
	v_pk_fma_f32 v[24:25], v[40:41], v[8:9], v[24:25] op_sel_hi:[1,0,1] neg_lo:[0,0,1] neg_hi:[0,0,1]
	v_pk_fma_f32 v[62:63], v[62:63], v[8:9], v[64:65] op_sel_hi:[1,0,1] neg_lo:[0,0,1] neg_hi:[0,0,1]
	v_pk_mul_f32 v[64:65], v[76:77], v[10:11] op_sel_hi:[1,0]
	v_pk_mul_f32 v[26:27], v[26:27], v[10:11] op_sel_hi:[1,0]
	v_pk_fma_f32 v[60:61], v[60:61], v[8:9], v[64:65] op_sel_hi:[1,0,1] neg_lo:[0,0,1] neg_hi:[0,0,1]
	v_pk_fma_f32 v[26:27], v[42:43], v[8:9], v[26:27] op_sel_hi:[1,0,1] neg_lo:[0,0,1] neg_hi:[0,0,1]
	v_pk_fma_f32 v[50:51], v[60:61], v[60:61], v[50:51]
	v_mul_f32_e32 v64, v61, v61
	v_pk_add_f32 v[50:51], v[64:65], v[50:51] op_sel_hi:[0,1]
	v_pk_fma_f32 v[50:51], v[62:63], v[62:63], v[50:51]
	v_mul_f32_e32 v64, v63, v63
	v_pk_add_f32 v[50:51], v[64:65], v[50:51] op_sel_hi:[0,1]
	v_pk_fma_f32 v[32:33], v[16:17], v[16:17], v[50:51]
	v_pk_mul_f32 v[30:31], v[30:31], v[10:11] op_sel_hi:[1,0]
	v_pk_add_f32 v[32:33], v[34:35], v[32:33] op_sel_hi:[0,1]
	v_pk_fma_f32 v[32:33], v[18:19], v[18:19], v[32:33]
	v_mul_f32_e32 v34, v19, v19
	v_pk_add_f32 v[32:33], v[34:35], v[32:33] op_sel_hi:[0,1]
	v_pk_fma_f32 v[32:33], v[20:21], v[20:21], v[32:33]
	v_mul_f32_e32 v34, v21, v21
	v_pk_add_f32 v[32:33], v[34:35], v[32:33] op_sel_hi:[0,1]
	v_pk_fma_f32 v[32:33], v[22:23], v[22:23], v[32:33]
	v_mul_f32_e32 v34, v23, v23
	v_pk_add_f32 v[32:33], v[34:35], v[32:33] op_sel_hi:[0,1]
	v_pk_fma_f32 v[32:33], v[24:25], v[24:25], v[32:33]
	v_mul_f32_e32 v34, v25, v25
	v_pk_add_f32 v[32:33], v[34:35], v[32:33] op_sel_hi:[0,1]
	v_pk_fma_f32 v[32:33], v[26:27], v[26:27], v[32:33]
	v_mul_f32_e32 v34, v27, v27
	v_pk_mul_f32 v[10:11], v[28:29], v[10:11] op_sel_hi:[1,0]
	v_pk_add_f32 v[32:33], v[34:35], v[32:33] op_sel_hi:[0,1]
	v_pk_fma_f32 v[30:31], v[46:47], v[8:9], v[30:31] op_sel_hi:[1,0,1] neg_lo:[0,0,1] neg_hi:[0,0,1]
	v_pk_fma_f32 v[8:9], v[44:45], v[8:9], v[10:11] op_sel_hi:[1,0,1] neg_lo:[0,0,1] neg_hi:[0,0,1]
	s_waitcnt vmcnt(1)
	v_lshlrev_b32_e32 v12, 16, v90
	v_pk_fma_f32 v[10:11], v[8:9], v[8:9], v[32:33]
	v_mul_f32_e32 v28, v9, v9
	v_pk_add_f32 v[10:11], v[28:29], v[10:11] op_sel_hi:[0,1]
	v_pk_fma_f32 v[10:11], v[30:31], v[30:31], v[10:11]
	v_mul_f32_e32 v28, v31, v31
	v_pk_add_f32 v[10:11], v[28:29], v[10:11] op_sel_hi:[0,1]
	v_mov_b32_e32 v11, v10
	s_nop 1
	v_permlane32_swap_b32_e32 v10, v11
	v_add_f32_e32 v10, v10, v11
	v_fmamk_f32 v10, v10, 0x3c800000, v201
	v_mul_f32_e32 v11, 0x4b800000, v10
	v_cmp_gt_f32_e32 vcc, s87, v10
	v_and_b32_e32 v13, 0xffff0000, v90
	v_lshl_add_u64 v[2:3], v[2:3], 0, v[88:89]
	v_cndmask_b32_e32 v10, v10, v11, vcc
	v_rsq_f32_e32 v28, v10
	v_lshlrev_b32_e32 v10, 16, v91
	v_and_b32_e32 v11, 0xffff0000, v91
	s_mov_b32 s6, 0x120000
	v_mul_f32_e32 v29, 0x45800000, v28
	v_cndmask_b32_e32 v28, v28, v29, vcc
	v_mul_f32_e32 v28, v80, v28
	v_pk_mul_f32 v[32:33], v[48:49], v[28:29] op_sel_hi:[1,0]
	s_waitcnt vmcnt(0)
	v_pk_mul_f32 v[4:5], v[4:5], v[32:33]
	s_nop 0
	v_pk_mul_f32 v[4:5], v[4:5], v[12:13]
	v_pk_mul_f32 v[12:13], v[14:15], v[28:29] op_sel_hi:[1,0]
	v_cvt_pk_bf16_f32 v4, v4, v5
	v_pk_mul_f32 v[6:7], v[6:7], v[12:13]
	v_pk_mul_f32 v[14:15], v[52:53], v[28:29] op_sel_hi:[1,0]
	v_pk_mul_f32 v[6:7], v[6:7], v[10:11]
	s_nop 0
	v_cvt_pk_bf16_f32 v5, v6, v7
	global_store_dwordx2 v[2:3], v[4:5], off
	global_load_dwordx2 v[10:11], v[0:1], off offset:16
	s_nop 0
	global_load_dwordx4 v[4:7], v192, s[4:5] offset:32
	s_waitcnt vmcnt(1)
	v_lshlrev_b32_e32 v12, 16, v10
	v_and_b32_e32 v13, 0xffff0000, v10
	s_waitcnt vmcnt(0)
; DI unsigned pk2(float a, float b) { f2_t v = {a, b}; bf2_t r = __builtin_convertvector(v, bf2_t); return __builtin_bit_cast(unsigned, r); }
; DI float bf2f(bf16_t v) { return __uint_as_float(((unsigned)v) << 16); }
; template <int KIND>
; DI void attn_unit(const Params& p, int l, int b, int head, int qt, int qcol, int kcol, int vfeat, int gcol, int mixcol,
;                   int t1, int n1, int t2, int n2, char* smem) {
;     ...
; #pragma unroll
;         for (int t = 0; t < 2; ++t)
; #pragma unroll
;             for (int q = 0; q < 4; ++q) {
;                 const int f = 32 * t + 8 * q + 4 * h;
;                 const float4 w4 = *(const float4*)(sw + f);
;                 const uint2 gg = *(const uint2*)(grow + f);
;                 const float g0 = bf2f((bf16_t)(gg.x & 0xffff)), g1 = bf2f((bf16_t)(gg.x >> 16)), g2 = bf2f((bf16_t)(gg.y & 0xffff)), g3 = bf2f((bf16_t)(gg.y >> 16));
;                 uint2 o;
;                 o.x = pk2(O0[t][4 * q + 0] * rstd * w4.x * g0, O0[t][4 * q + 1] * rstd * w4.y * g1);
;                 o.y = pk2(O0[t][4 * q + 2] * rstd * w4.z * g2, O0[t][4 * q + 3] * rstd * w4.w * g3);
;                 *(uint2*)(orow + (size_t)t * NTOK * 32 + 8 * q + 4 * h) = o;
;             }
	v_pk_mul_f32 v[4:5], v[4:5], v[14:15]
	v_lshlrev_b32_e32 v10, 16, v11
	v_pk_mul_f32 v[4:5], v[4:5], v[12:13]
	v_pk_mul_f32 v[12:13], v[54:55], v[28:29] op_sel_hi:[1,0]
	v_and_b32_e32 v11, 0xffff0000, v11
	v_pk_mul_f32 v[6:7], v[12:13], v[6:7]
	v_cvt_pk_bf16_f32 v4, v4, v5
	v_pk_mul_f32 v[6:7], v[6:7], v[10:11]
	v_pk_mul_f32 v[14:15], v[56:57], v[28:29] op_sel_hi:[1,0]
	v_cvt_pk_bf16_f32 v5, v6, v7
	global_store_dwordx2 v[2:3], v[4:5], off offset:16
	global_load_dwordx2 v[10:11], v[0:1], off offset:32
	s_nop 0
	global_load_dwordx4 v[4:7], v192, s[4:5] offset:64
	s_waitcnt vmcnt(1)
	v_lshlrev_b32_e32 v12, 16, v10
	v_and_b32_e32 v13, 0xffff0000, v10
	s_waitcnt vmcnt(0)
	v_pk_mul_f32 v[4:5], v[14:15], v[4:5]
	v_lshlrev_b32_e32 v10, 16, v11
	v_pk_mul_f32 v[4:5], v[4:5], v[12:13]
	v_pk_mul_f32 v[12:13], v[58:59], v[28:29] op_sel_hi:[1,0]
	v_and_b32_e32 v11, 0xffff0000, v11
	v_pk_mul_f32 v[6:7], v[12:13], v[6:7]
	v_cvt_pk_bf16_f32 v4, v4, v5
	v_pk_mul_f32 v[6:7], v[6:7], v[10:11]
	v_pk_mul_f32 v[12:13], v[60:61], v[28:29] op_sel_hi:[1,0]
	v_cvt_pk_bf16_f32 v5, v6, v7
	global_store_dwordx2 v[2:3], v[4:5], off offset:32
	global_load_dwordx2 v[10:11], v[0:1], off offset:48
	s_nop 0
	global_load_dwordx4 v[4:7], v192, s[4:5] offset:96
	v_pk_mul_f32 v[14:15], v[62:63], v[28:29] op_sel_hi:[1,0]
	s_waitcnt vmcnt(1)
	v_lshlrev_b32_e32 v32, 16, v10
	v_and_b32_e32 v33, 0xffff0000, v10
	v_lshlrev_b32_e32 v10, 16, v11
	v_and_b32_e32 v11, 0xffff0000, v11
	s_waitcnt vmcnt(0)
	v_pk_mul_f32 v[4:5], v[12:13], v[4:5]
	v_pk_mul_f32 v[6:7], v[14:15], v[6:7]
	v_pk_mul_f32 v[4:5], v[4:5], v[32:33]
	v_pk_mul_f32 v[6:7], v[6:7], v[10:11]
	v_cvt_pk_bf16_f32 v4, v4, v5
	v_cvt_pk_bf16_f32 v5, v6, v7
	global_store_dwordx2 v[2:3], v[4:5], off offset:48
	global_load_dwordx2 v[10:11], v[0:1], off offset:64
	s_nop 0
	global_load_dwordx4 v[4:7], v192, s[4:5] offset:128
	v_add_co_u32_e32 v12, vcc, s6, v2
	v_pk_mul_f32 v[14:15], v[18:19], v[28:29] op_sel_hi:[1,0]
	s_nop 0
	v_addc_co_u32_e32 v13, vcc, 0, v3, vcc
	v_pk_mul_f32 v[2:3], v[16:17], v[28:29] op_sel_hi:[1,0]
	s_waitcnt vmcnt(1)
	v_lshlrev_b32_e32 v16, 16, v10
	v_and_b32_e32 v17, 0xffff0000, v10
	v_lshlrev_b32_e32 v10, 16, v11
	v_and_b32_e32 v11, 0xffff0000, v11
	s_waitcnt vmcnt(0)
	v_pk_mul_f32 v[2:3], v[2:3], v[4:5]
	v_pk_mul_f32 v[4:5], v[14:15], v[6:7]
	v_pk_mul_f32 v[2:3], v[2:3], v[16:17]
	v_pk_mul_f32 v[4:5], v[4:5], v[10:11]
	v_cvt_pk_bf16_f32 v2, v2, v3
	v_cvt_pk_bf16_f32 v3, v4, v5
	global_store_dwordx2 v[12:13], v[2:3], off
	global_load_dwordx2 v[6:7], v[0:1], off offset:80
	s_nop 0
	global_load_dwordx4 v[2:5], v192, s[4:5] offset:160
	v_pk_mul_f32 v[10:11], v[20:21], v[28:29] op_sel_hi:[1,0]
	v_pk_mul_f32 v[14:15], v[22:23], v[28:29] op_sel_hi:[1,0]
	s_waitcnt vmcnt(1)
	v_lshlrev_b32_e32 v16, 16, v6
	v_and_b32_e32 v17, 0xffff0000, v6
	v_lshlrev_b32_e32 v6, 16, v7
	v_and_b32_e32 v7, 0xffff0000, v7
	s_waitcnt vmcnt(0)
	v_pk_mul_f32 v[2:3], v[10:11], v[2:3]
	v_pk_mul_f32 v[4:5], v[14:15], v[4:5]
	v_pk_mul_f32 v[2:3], v[2:3], v[16:17]
	v_pk_mul_f32 v[4:5], v[4:5], v[6:7]
	v_cvt_pk_bf16_f32 v2, v2, v3
	v_cvt_pk_bf16_f32 v3, v4, v5
	global_store_dwordx2 v[12:13], v[2:3], off offset:16
	global_load_dwordx2 v[6:7], v[0:1], off offset:96
	s_nop 0
	global_load_dwordx4 v[2:5], v192, s[4:5] offset:192
	v_pk_mul_f32 v[10:11], v[24:25], v[28:29] op_sel_hi:[1,0]
	v_pk_mul_f32 v[14:15], v[26:27], v[28:29] op_sel_hi:[1,0]
	s_waitcnt vmcnt(1)
	v_lshlrev_b32_e32 v16, 16, v6
	v_and_b32_e32 v17, 0xffff0000, v6
	v_lshlrev_b32_e32 v6, 16, v7
	v_and_b32_e32 v7, 0xffff0000, v7
	s_waitcnt vmcnt(0)
	v_pk_mul_f32 v[2:3], v[10:11], v[2:3]
	v_pk_mul_f32 v[4:5], v[14:15], v[4:5]
	v_pk_mul_f32 v[2:3], v[2:3], v[16:17]
	v_pk_mul_f32 v[4:5], v[4:5], v[6:7]
	v_cvt_pk_bf16_f32 v2, v2, v3
	v_cvt_pk_bf16_f32 v3, v4, v5
	global_store_dwordx2 v[12:13], v[2:3], off offset:32
	global_load_dwordx2 v[4:5], v[0:1], off offset:112
	s_nop 0
	global_load_dwordx4 v[0:3], v192, s[4:5] offset:224
	v_pk_mul_f32 v[6:7], v[8:9], v[28:29] op_sel_hi:[1,0]
	v_pk_mul_f32 v[8:9], v[30:31], v[28:29] op_sel_hi:[1,0]
	s_mov_b64 s[4:5], 0
	s_waitcnt vmcnt(1)
	v_lshlrev_b32_e32 v10, 16, v4
	v_and_b32_e32 v11, 0xffff0000, v4
	v_lshlrev_b32_e32 v4, 16, v5
	v_and_b32_e32 v5, 0xffff0000, v5
	s_waitcnt vmcnt(0)
	v_pk_mul_f32 v[0:1], v[6:7], v[0:1]
	v_pk_mul_f32 v[2:3], v[8:9], v[2:3]
	v_pk_mul_f32 v[0:1], v[0:1], v[10:11]
	v_pk_mul_f32 v[2:3], v[2:3], v[4:5]
	v_cvt_pk_bf16_f32 v0, v0, v1
	v_cvt_pk_bf16_f32 v1, v2, v3
	global_store_dwordx2 v[12:13], v[0:1], off offset:48
	s_branch .LBB0_71

; DI int otid() { int t = threadIdx.x; asm volatile("" : "+v"(t)); return t; }
; template <bool VMODE, int TJ>
; DI void gemm_mainloop(const bf16_t* __restrict__ W, const bf16_t* __restrict__ X, int NW, char* smem, f32x16 (&acc)[2][TJ]) {
;     constexpr int XROWS = 64 * TJ, STAGE = (128 + XROWS) * 64, NPW = 2 + TJ;
;     const int tid = otid(), lane = tid & 63, wave = tid >> 6, r = lane & 31, h = lane >> 5, wf = wave & 1, wt = wave >> 1;
;     const int goff = (16 * wave + (lane >> 2)) * 32 + (((lane & 3) ^ (lane >> 4)) << 3);
;     const bf16_t* wp = W + goff;
;     const bf16_t* xp = X + goff;
;     const size_t wks = (size_t)NW * 32, xks = (size_t)NTOK * 32;
;     char* ld = smem + tid * 16;
;     ...
;     const int xr = (r >> 2) & 3;
;     const int fo0 = r * 64 + (((0 + h) ^ xr) << 4), fo1 = r * 64 + (((2 + h) ^ xr) << 4);
;     __syncthreads();
; DI void inproj_phase(const Params& p, int l, char* smem) {
;     ...
;         const int n0 = nt * 128;
;         const bf16_t* W = p.wtin + (size_t)l * INW * D + (size_t)n0 * 32;
;         const bf16_t* X = p.hmix + (size_t)mtile * 256 * 32;
;         f32x16 acc[2][4];
;         zero_acc<4>(acc);
;         int vf0 = -1;
;         if (n0 >= 512 && n0 < 768) vf0 = n0 - 512;
;         else if (n0 >= 1536 && n0 < 1664) vf0 = 256 + (n0 - 1536);
;         else if (n0 >= 2816 && n0 < 3200) vf0 = 384 + (n0 - 2816);
;         if (vf0 >= 0) { gemm_mainloop<true, 4>(W, X, INW, smem, acc); epi_v(p, mtile, vf0, acc, smem); }
.LBB0_200:
	s_load_dwordx2 s[4:5], s[0:1], 0xd0
	s_load_dwordx2 s[6:7], s[0:1], 0xb8
	s_mul_hi_i32 s47, s50, 0x38e38e39
	s_waitcnt lgkmcnt(0)
	s_add_u32 s8, s4, s63
	s_addc_u32 s9, s5, s62
	s_ashr_i32 s59, s58, 31
	s_lshl_b64 s[4:5], s[58:59], 6
	s_add_u32 s52, s8, s4
	s_addc_u32 s53, s9, s5
	s_ashr_i32 s51, s50, 31
	s_lshl_b64 s[4:5], s[50:51], 14
	s_add_u32 s56, s6, s4
	s_addc_u32 s57, s7, s5
	s_mov_b64 s[4:5], -1
	s_cmp_lt_i32 s46, 0
	s_cbranch_scc0 .LBB0_287
	v_mov_b32_e32 v4, v200
	s_movk_i32 s4, 0xffe0
	v_bfe_u32 v1, v4, 4, 2
	v_bitop3_b32 v1, v1, v4, 3 bitop3:0x78
	v_lshlrev_b32_e32 v0, 3, v4
	v_lshlrev_b32_e32 v1, 3, v1
	v_and_or_b32 v0, v0, s4, v1
	v_bfe_u32 v5, v4, 5, 1
	v_ashrrev_i32_e32 v1, 31, v0
	v_lshl_add_u32 v130, v4, 4, 32
	v_bfe_u32 v7, v4, 2, 2
	v_lshlrev_b64 v[128:129], 1, v[0:1]
	v_bitop3_b32 v9, v5, v7, 2 bitop3:0x36
	v_readfirstlane_b32 s4, v130
	v_add_u32_e32 v7, 0x1000, v130
	v_lshl_add_u64 v[0:1], s[52:53], 0, v[128:129]
	v_lshrrev_b32_e32 v6, 2, v4
	s_mov_b32 m0, s4
	v_readfirstlane_b32 s4, v7
	v_lshlrev_b32_e32 v8, 6, v4
	v_bitop3_b32 v6, v5, v6, 3 bitop3:0x78
	s_barrier
	global_load_lds_dwordx4 v[0:1], off
	v_lshl_add_u64 v[4:5], v[0:1], 0, s[26:27]
	s_mov_b32 m0, s4
	v_add_u32_e32 v7, 0x3000, v130
	global_load_lds_dwordx4 v[4:5], off
	v_add_u32_e32 v4, 0x2000, v130
	v_lshl_add_u64 v[2:3], s[56:57], 0, v[128:129]
	v_readfirstlane_b32 s4, v4
	s_mov_b32 m0, s4
	v_readfirstlane_b32 s4, v7
	v_add_u32_e32 v7, 0x4000, v130
	global_load_lds_dwordx4 v[2:3], off
	v_lshl_add_u64 v[4:5], v[2:3], 0, s[26:27]
	s_mov_b32 m0, s4
	v_readfirstlane_b32 s4, v7
	v_add_u32_e32 v7, 0x5000, v130
	global_load_lds_dwordx4 v[4:5], off
	v_lshl_add_u64 v[4:5], v[2:3], 0, s[16:17]
	s_mov_b32 m0, s4
	v_readfirstlane_b32 s4, v7
	global_load_lds_dwordx4 v[4:5], off
	v_lshl_add_u64 v[4:5], v[2:3], 0, s[90:91]
	s_mov_b32 m0, s4
	s_mov_b64 s[4:5], 0x38000
	global_load_lds_dwordx4 v[4:5], off
	v_and_b32_e32 v10, 0x7c0, v8
	v_lshl_add_u64 v[4:5], v[0:1], 0, s[4:5]
	s_mov_b64 s[4:5], 0x120000
	v_add_u32_e32 v11, 0x6000, v130
	v_lshl_or_b32 v131, v6, 4, v10
	v_lshl_add_u64 v[6:7], v[2:3], 0, s[4:5]
	v_readfirstlane_b32 s4, v11
	s_mov_b32 m0, s4
	s_mov_b64 s[4:5], 0x39000
	global_load_lds_dwordx4 v[4:5], off
	v_add_u32_e32 v4, 0x7000, v130
	v_lshl_add_u64 v[0:1], v[0:1], 0, s[4:5]
	v_readfirstlane_b32 s4, v4
	s_mov_b32 m0, s4
	v_add_u32_e32 v4, 0x9000, v130
	global_load_lds_dwordx4 v[0:1], off
	v_add_u32_e32 v0, 0x8000, v130
	s_mov_b32 s8, 2
	v_readfirstlane_b32 s4, v0
	s_mov_b32 m0, s4
	s_mov_b64 s[4:5], 0x121000
	v_lshl_add_u64 v[0:1], v[2:3], 0, s[4:5]
	v_readfirstlane_b32 s4, v4
	global_load_lds_dwordx4 v[6:7], off
	s_mov_b32 m0, s4
	s_mov_b64 s[4:5], 0x122000
	v_add_u32_e32 v4, 0xa000, v130
	global_load_lds_dwordx4 v[0:1], off
	v_lshl_add_u64 v[0:1], v[2:3], 0, s[4:5]
	v_readfirstlane_b32 s4, v4
	s_mov_b32 m0, s4
	s_mov_b64 s[4:5], 0x123000
	global_load_lds_dwordx4 v[0:1], off
	v_lshl_add_u64 v[0:1], v[2:3], 0, s[4:5]
	v_add_u32_e32 v2, 0xb000, v130
	v_lshl_or_b32 v132, v9, 4, v10
	v_readfirstlane_b32 s4, v2
	s_mov_b32 m0, s4
	v_and_b32_e32 v134, 0x1000, v8
	global_load_lds_dwordx4 v[0:1], off
	v_mov_b32_e32 v0, 0
	v_and_b32_e32 v133, 0xffffe000, v8
	s_mov_b32 s28, 0
	s_mov_b32 s9, 30
	s_mov_b64 s[4:5], s[52:53]
	s_mov_b64 s[6:7], s[56:57]
	v_mov_b32_e32 v1, v0
	v_mov_b32_e32 v2, v0
	v_mov_b32_e32 v3, v0
	v_mov_b32_e32 v4, v0
	v_mov_b32_e32 v5, v0
	v_mov_b32_e32 v6, v0
	v_mov_b32_e32 v7, v0
	v_mov_b32_e32 v8, v0
	v_mov_b32_e32 v9, v0
	v_mov_b32_e32 v10, v0
	v_mov_b32_e32 v11, v0
	v_mov_b32_e32 v12, v0
	v_mov_b32_e32 v13, v0
	v_mov_b32_e32 v14, v0
	v_mov_b32_e32 v15, v0
	v_mov_b32_e32 v32, v0
	v_mov_b32_e32 v33, v0
	v_mov_b32_e32 v34, v0
	v_mov_b32_e32 v35, v0
	v_mov_b32_e32 v36, v0
	v_mov_b32_e32 v37, v0
	v_mov_b32_e32 v38, v0
	v_mov_b32_e32 v39, v0
	v_mov_b32_e32 v40, v0
	v_mov_b32_e32 v41, v0
	v_mov_b32_e32 v42, v0
	v_mov_b32_e32 v43, v0
	v_mov_b32_e32 v44, v0
	v_mov_b32_e32 v45, v0
	v_mov_b32_e32 v46, v0
	v_mov_b32_e32 v47, v0
	v_mov_b32_e32 v64, v0
	v_mov_b32_e32 v65, v0
	v_mov_b32_e32 v66, v0
	v_mov_b32_e32 v67, v0
	v_mov_b32_e32 v68, v0
	v_mov_b32_e32 v69, v0
	v_mov_b32_e32 v70, v0
	v_mov_b32_e32 v71, v0
	v_mov_b32_e32 v72, v0
	v_mov_b32_e32 v73, v0
	v_mov_b32_e32 v74, v0
	v_mov_b32_e32 v75, v0
	v_mov_b32_e32 v76, v0
	v_mov_b32_e32 v77, v0
	v_mov_b32_e32 v78, v0
	v_mov_b32_e32 v79, v0
	v_mov_b32_e32 v96, v0
	v_mov_b32_e32 v97, v0
	v_mov_b32_e32 v98, v0
	v_mov_b32_e32 v99, v0
	v_mov_b32_e32 v100, v0
	v_mov_b32_e32 v101, v0
	v_mov_b32_e32 v102, v0
	v_mov_b32_e32 v103, v0
	v_mov_b32_e32 v104, v0
	v_mov_b32_e32 v105, v0
	v_mov_b32_e32 v106, v0
	v_mov_b32_e32 v107, v0
	v_mov_b32_e32 v108, v0
	v_mov_b32_e32 v109, v0
	v_mov_b32_e32 v110, v0
	v_mov_b32_e32 v111, v0
	v_mov_b32_e32 v16, v0
	v_mov_b32_e32 v17, v0
	v_mov_b32_e32 v18, v0
	v_mov_b32_e32 v19, v0
	v_mov_b32_e32 v20, v0
	v_mov_b32_e32 v21, v0
	v_mov_b32_e32 v22, v0
	v_mov_b32_e32 v23, v0
	v_mov_b32_e32 v24, v0
	v_mov_b32_e32 v25, v0
	v_mov_b32_e32 v26, v0
	v_mov_b32_e32 v27, v0
	v_mov_b32_e32 v28, v0
	v_mov_b32_e32 v29, v0
	v_mov_b32_e32 v30, v0
	v_mov_b32_e32 v31, v0
	v_mov_b32_e32 v48, v0
	v_mov_b32_e32 v49, v0
	v_mov_b32_e32 v50, v0
	v_mov_b32_e32 v51, v0
	v_mov_b32_e32 v52, v0
	v_mov_b32_e32 v53, v0
	v_mov_b32_e32 v54, v0
	v_mov_b32_e32 v55, v0
	v_mov_b32_e32 v56, v0
	v_mov_b32_e32 v57, v0
	v_mov_b32_e32 v58, v0
	v_mov_b32_e32 v59, v0
	v_mov_b32_e32 v60, v0
	v_mov_b32_e32 v61, v0
	v_mov_b32_e32 v62, v0
	v_mov_b32_e32 v63, v0
	v_mov_b32_e32 v80, v0
	v_mov_b32_e32 v81, v0
	v_mov_b32_e32 v82, v0
	v_mov_b32_e32 v83, v0
	v_mov_b32_e32 v84, v0
	v_mov_b32_e32 v85, v0
	v_mov_b32_e32 v86, v0
	v_mov_b32_e32 v87, v0
	v_mov_b32_e32 v88, v0
	v_mov_b32_e32 v89, v0
	v_mov_b32_e32 v90, v0
	v_mov_b32_e32 v91, v0
	v_mov_b32_e32 v92, v0
	v_mov_b32_e32 v93, v0
	v_mov_b32_e32 v94, v0
	v_mov_b32_e32 v95, v0
	v_mov_b32_e32 v112, v0
	v_mov_b32_e32 v113, v0
	v_mov_b32_e32 v114, v0
	v_mov_b32_e32 v115, v0
	v_mov_b32_e32 v116, v0
	v_mov_b32_e32 v117, v0
	v_mov_b32_e32 v118, v0
	v_mov_b32_e32 v119, v0
	v_mov_b32_e32 v120, v0
	v_mov_b32_e32 v121, v0
	v_mov_b32_e32 v122, v0
	v_mov_b32_e32 v123, v0
	v_mov_b32_e32 v124, v0
	v_mov_b32_e32 v125, v0
	v_mov_b32_e32 v126, v0
	v_mov_b32_e32 v127, v0
	v_readfirstlane_b32 s100, v130
	v_add_u32_e32 v170, 0x38000, v128
	v_add_u32_e32 v171, 0x39000, v128
	v_add_u32_e32 v172, 0x120000, v128
	v_add_u32_e32 v173, 0x121000, v128
	v_add_u32_e32 v174, 0x122000, v128
	v_add_u32_e32 v175, 0x123000, v128
	s_mul_i32 s29, s28, 0x6000
	s_add_i32 s29, s29, 32
	v_add_u32_e32 v135, s29, v134
	v_add_u32_e32 v168, s29, v133
	v_add_u32_e32 v140, v135, v131
	v_add_u32_e32 v156, v168, v131
	s_waitcnt vmcnt(6)
	s_barrier
; #define MFMA(a, b, c) __builtin_amdgcn_mfma_f32_32x32x16_bf16((a), (b), (c), 0, 0, 0)
; #define G_ISSUE(ks_, buf_) do { \
;     const bf16_t* wq_ = wp + (ks_) * wks; const bf16_t* xq_ = xp + (ks_) * xks; char* lb_ = ld + (buf_) * STAGE; \
;     dma16(wq_, lb_); dma16(wq_ + 2048, lb_ + 4096); \
;     _Pragma("unroll") for (int i_ = 0; i_ < TJ; ++i_) dma16(xq_ + i_ * 2048, lb_ + 8192 + i_ * 4096); } while (0)
; template <bool VMODE, int TJ>
; DI void gemm_mainloop(const bf16_t* __restrict__ W, const bf16_t* __restrict__ X, int NW, char* smem, f32x16 (&acc)[2][TJ]) {
;     ...
;         for (int ks = 0; ks < 32; ++ks) {
;             if (ks < 31) asm volatile("s_waitcnt vmcnt(6)" ::: "memory");
;             else asm volatile("s_waitcnt vmcnt(0)" ::: "memory");
;             __builtin_amdgcn_s_barrier();
;             const char* sw = smem + bc * STAGE + wf * 64 * 64;
;             const char* sx = smem + bc * STAGE + 8192 + wt * (32 * TJ) * 64;
;             bf16x8 fw[2], fx[TJ], gw[2], gx[TJ];
; #pragma unroll
;             for (int i = 0; i < 2; ++i) fw[i] = *(const bf16x8*)(sw + i * 32 * 64 + fo0);
; #pragma unroll
;             for (int j = 0; j < TJ; ++j) fx[j] = *(const bf16x8*)(sx + j * 32 * 64 + fo0);
;             __builtin_amdgcn_sched_barrier(0);
;             if (ks + 2 < 32) G_ISSUE(ks + 2, bn);
;             __builtin_amdgcn_sched_barrier(0);
; #pragma unroll
;             for (int i = 0; i < 2; ++i) gw[i] = *(const bf16x8*)(sw + i * 32 * 64 + fo1);
; #pragma unroll
;             for (int j = 0; j < TJ; ++j) gx[j] = *(const bf16x8*)(sx + j * 32 * 64 + fo1);
; #pragma unroll
;             for (int i = 0; i < 2; ++i)
; #pragma unroll
;                 for (int j = 0; j < TJ; ++j) acc[i][j] = VMODE ? MFMA(fx[j], fw[i], acc[i][j]) : MFMA(fw[i], fx[j], acc[i][j]);
; #pragma unroll
;             for (int i = 0; i < 2; ++i)
; #pragma unroll
;                 for (int j = 0; j < TJ; ++j) acc[i][j] = VMODE ? MFMA(gx[j], gw[i], acc[i][j]) : MFMA(gw[i], gx[j], acc[i][j]);
;             bc = (bc == 2) ? 0 : bc + 1; bn = (bn == 2) ? 0 : bn + 1;
;         }
	ds_read_b128 v[136:139], v140
	ds_read_b128 v[140:143], v140 offset:2048
	ds_read_b128 v[144:147], v156 offset:8192
	ds_read_b128 v[148:151], v156 offset:10240
	ds_read_b128 v[152:155], v156 offset:12288
	ds_read_b128 v[156:159], v156 offset:14336
	s_mul_i32 s29, s8, 0x6000
	s_add_i32 s101, s29, s100
	s_add_i32 s29, s28, 1
	s_cmp_lg_u32 s28, 2
	s_cselect_b32 s28, s29, 0
	s_add_i32 s29, s8, 1
	s_cmp_lg_u32 s8, 2
	s_cselect_b32 s8, s29, 0
	s_add_i32 s9, s9, -1
	s_add_u32 s6, s6, 0x120000
	s_addc_u32 s7, s7, 0
	s_add_u32 s4, s4, 0x38000
	s_addc_u32 s5, s5, 0
	v_add_u32_e32 v169, v135, v132
	v_add_u32_e32 v192, v168, v132
	s_mov_b32 m0, s101
	s_waitcnt lgkmcnt(0)
	v_mfma_f32_32x32x16_bf16 v[112:127], v[136:139], v[144:147], v[112:127]
	global_load_lds_dwordx4 v170, s[4:5]
	s_add_u32 m0, s101, 0x1000
	ds_read_b128 v[160:163], v169
	v_mfma_f32_32x32x16_bf16 v[80:95], v[136:139], v[148:151], v[80:95]
	global_load_lds_dwordx4 v171, s[4:5]
	s_add_u32 m0, s101, 0x2000
	ds_read_b128 v[164:167], v192 offset:8192
	v_mfma_f32_32x32x16_bf16 v[48:63], v[136:139], v[152:155], v[48:63]
	global_load_lds_dwordx4 v172, s[6:7]
	s_add_u32 m0, s101, 0x3000
	ds_read_b128 v[176:179], v169 offset:2048
	v_mfma_f32_32x32x16_bf16 v[16:31], v[136:139], v[156:159], v[16:31]
	global_load_lds_dwordx4 v173, s[6:7]
	s_add_u32 m0, s101, 0x4000
	ds_read_b128 v[180:183], v192 offset:10240
	v_mfma_f32_32x32x16_bf16 v[96:111], v[140:143], v[144:147], v[96:111]
	global_load_lds_dwordx4 v174, s[6:7]
	s_add_u32 m0, s101, 0x5000
	ds_read_b128 v[184:187], v192 offset:12288
	v_mfma_f32_32x32x16_bf16 v[64:79], v[140:143], v[148:151], v[64:79]
	global_load_lds_dwordx4 v175, s[6:7]
	ds_read_b128 v[188:191], v192 offset:14336
	v_mfma_f32_32x32x16_bf16 v[32:47], v[140:143], v[152:155], v[32:47]
	v_mfma_f32_32x32x16_bf16 v[0:15], v[140:143], v[156:159], v[0:15]
.LBB0_202:
	s_mul_i32 s29, s28, 0x6000
	s_add_i32 s29, s29, 32
	v_add_u32_e32 v135, s29, v134
	v_add_u32_e32 v168, s29, v133
	v_add_u32_e32 v140, v135, v131
	v_add_u32_e32 v156, v168, v131
	s_waitcnt vmcnt(6)
	s_waitcnt lgkmcnt(0)
	s_barrier
	ds_read_b128 v[136:139], v140
	ds_read_b128 v[140:143], v140 offset:2048
	ds_read_b128 v[144:147], v156 offset:8192
	ds_read_b128 v[148:151], v156 offset:10240
	ds_read_b128 v[152:155], v156 offset:12288
	ds_read_b128 v[156:159], v156 offset:14336
	s_mul_i32 s29, s8, 0x6000
	s_add_i32 s101, s29, s100
	s_add_i32 s29, s28, 1
	s_cmp_lg_u32 s28, 2
	s_cselect_b32 s28, s29, 0
	s_add_i32 s29, s8, 1
	s_cmp_lg_u32 s8, 2
	s_cselect_b32 s8, s29, 0
	s_add_i32 s9, s9, -1
	s_add_u32 s6, s6, 0x120000
	s_addc_u32 s7, s7, 0
	s_add_u32 s4, s4, 0x38000
	s_addc_u32 s5, s5, 0
	v_add_u32_e32 v169, v135, v132
	v_add_u32_e32 v192, v168, v132
	s_mov_b32 m0, s101
	v_mfma_f32_32x32x16_bf16 v[112:127], v[160:163], v[164:167], v[112:127]
	global_load_lds_dwordx4 v170, s[4:5]
	s_add_u32 m0, s101, 0x1000
	v_mfma_f32_32x32x16_bf16 v[80:95], v[160:163], v[180:183], v[80:95]
	global_load_lds_dwordx4 v171, s[4:5]
	s_add_u32 m0, s101, 0x2000
	v_mfma_f32_32x32x16_bf16 v[48:63], v[160:163], v[184:187], v[48:63]
	global_load_lds_dwordx4 v172, s[6:7]
	s_add_u32 m0, s101, 0x3000
	v_mfma_f32_32x32x16_bf16 v[16:31], v[160:163], v[188:191], v[16:31]
	global_load_lds_dwordx4 v173, s[6:7]
	s_add_u32 m0, s101, 0x4000
	v_mfma_f32_32x32x16_bf16 v[96:111], v[176:179], v[164:167], v[96:111]
	global_load_lds_dwordx4 v174, s[6:7]
	s_add_u32 m0, s101, 0x5000
	v_mfma_f32_32x32x16_bf16 v[64:79], v[176:179], v[180:183], v[64:79]
	global_load_lds_dwordx4 v175, s[6:7]
	v_mfma_f32_32x32x16_bf16 v[32:47], v[176:179], v[184:187], v[32:47]
	v_mfma_f32_32x32x16_bf16 v[0:15], v[176:179], v[188:191], v[0:15]
	s_waitcnt lgkmcnt(0)
	v_mfma_f32_32x32x16_bf16 v[112:127], v[136:139], v[144:147], v[112:127]
	ds_read_b128 v[160:163], v169
	v_mfma_f32_32x32x16_bf16 v[80:95], v[136:139], v[148:151], v[80:95]
	ds_read_b128 v[164:167], v192 offset:8192
	v_mfma_f32_32x32x16_bf16 v[48:63], v[136:139], v[152:155], v[48:63]
	ds_read_b128 v[176:179], v169 offset:2048
	v_mfma_f32_32x32x16_bf16 v[16:31], v[136:139], v[156:159], v[16:31]
	ds_read_b128 v[180:183], v192 offset:10240
	v_mfma_f32_32x32x16_bf16 v[96:111], v[140:143], v[144:147], v[96:111]
	ds_read_b128 v[184:187], v192 offset:12288
	v_mfma_f32_32x32x16_bf16 v[64:79], v[140:143], v[148:151], v[64:79]
	ds_read_b128 v[188:191], v192 offset:14336
	v_mfma_f32_32x32x16_bf16 v[32:47], v[140:143], v[152:155], v[32:47]
	v_mfma_f32_32x32x16_bf16 v[0:15], v[140:143], v[156:159], v[0:15]
	s_cmp_lg_u32 s9, 0
	s_cbranch_scc1 .LBB0_202
; #define MFMA(a, b, c) __builtin_amdgcn_mfma_f32_32x32x16_bf16((a), (b), (c), 0, 0, 0)
; template <bool VMODE, int TJ>
; DI void gemm_mainloop(const bf16_t* __restrict__ W, const bf16_t* __restrict__ X, int NW, char* smem, f32x16 (&acc)[2][TJ]) {
;     ...
;         for (int ks = 0; ks < 32; ++ks) {
;             if (ks < 31) asm volatile("s_waitcnt vmcnt(6)" ::: "memory");
;             else asm volatile("s_waitcnt vmcnt(0)" ::: "memory");
;             __builtin_amdgcn_s_barrier();
;             const char* sw = smem + bc * STAGE + wf * 64 * 64;
;             const char* sx = smem + bc * STAGE + 8192 + wt * (32 * TJ) * 64;
;             bf16x8 fw[2], fx[TJ], gw[2], gx[TJ];
; #pragma unroll
;             for (int i = 0; i < 2; ++i) fw[i] = *(const bf16x8*)(sw + i * 32 * 64 + fo0);
; #pragma unroll
;             for (int j = 0; j < TJ; ++j) fx[j] = *(const bf16x8*)(sx + j * 32 * 64 + fo0);
;             __builtin_amdgcn_sched_barrier(0);
;             if (ks + 2 < 32) G_ISSUE(ks + 2, bn);
;             __builtin_amdgcn_sched_barrier(0);
; #pragma unroll
;             for (int i = 0; i < 2; ++i) gw[i] = *(const bf16x8*)(sw + i * 32 * 64 + fo1);
; #pragma unroll
;             for (int j = 0; j < TJ; ++j) gx[j] = *(const bf16x8*)(sx + j * 32 * 64 + fo1);
; #pragma unroll
;             for (int i = 0; i < 2; ++i)
; #pragma unroll
;                 for (int j = 0; j < TJ; ++j) acc[i][j] = VMODE ? MFMA(fx[j], fw[i], acc[i][j]) : MFMA(fw[i], fx[j], acc[i][j]);
; #pragma unroll
;             for (int i = 0; i < 2; ++i)
; #pragma unroll
;                 for (int j = 0; j < TJ; ++j) acc[i][j] = VMODE ? MFMA(gx[j], gw[i], acc[i][j]) : MFMA(gw[i], gx[j], acc[i][j]);
;             bc = (bc == 2) ? 0 : bc + 1; bn = (bn == 2) ? 0 : bn + 1;
;         }
;     }
; DI void epi_inproj(const Params& p, int l, int mtile, int n0, f32x16 (&acc)[2][4], char* smem) {
;     ...
;     if (n0 < 256) { type = 2; nwt = p.dqn + l * 32; rope = true; }
;     else if (n0 < 512) { type = 2; nwt = p.dkn + l * 32; rope = true; }
;     else if (n0 < 1024) { type = 1; }
;     else if (n0 < 1408) { type = 3; nwt = p.gqn + l * 64; rope = true; }
;     else if (n0 < 1536) { type = 3; nwt = p.gkn + l * 64; rope = true; }
;     else if (n0 < 2048) { type = 1; }
;     else if (n0 < 2432) { type = 3; nwt = p.nqn + l * 64; }
;     else if (n0 < 2816) { type = 3; nwt = p.nkn + l * 64; }
;     else { type = 1; }
	s_waitcnt lgkmcnt(0)
	v_mfma_f32_32x32x16_bf16 v[112:127], v[160:163], v[164:167], v[112:127]
	v_mfma_f32_32x32x16_bf16 v[80:95], v[160:163], v[180:183], v[80:95]
	v_mfma_f32_32x32x16_bf16 v[48:63], v[160:163], v[184:187], v[48:63]
	v_mfma_f32_32x32x16_bf16 v[16:31], v[160:163], v[188:191], v[16:31]
	v_mfma_f32_32x32x16_bf16 v[96:111], v[176:179], v[164:167], v[96:111]
	v_mfma_f32_32x32x16_bf16 v[64:79], v[176:179], v[180:183], v[64:79]
	v_mfma_f32_32x32x16_bf16 v[32:47], v[176:179], v[184:187], v[32:47]
	v_mfma_f32_32x32x16_bf16 v[0:15], v[176:179], v[188:191], v[0:15]
	v_add_u32_e32 v154, 32, v134
	v_add_u32_e32 v133, 32, v133
	v_add_u32_e32 v155, v154, v131
	v_add_u32_e32 v156, v133, v131
	s_waitcnt vmcnt(6)
	s_barrier
	ds_read_b128 v[134:137], v155
	ds_read_b128 v[138:141], v155 offset:2048
	ds_read_b128 v[128:131], v156 offset:8192
	ds_read_b128 v[142:145], v156 offset:10240
	ds_read_b128 v[146:149], v156 offset:12288
	ds_read_b128 v[150:153], v156 offset:14336
	v_add_u32_e32 v160, v154, v132
	s_waitcnt lgkmcnt(0)
	v_mfma_f32_32x32x16_bf16 v[112:127], v[134:137], v[128:131], v[112:127]
	v_add_u32_e32 v161, v133, v132
	v_mfma_f32_32x32x16_bf16 v[96:111], v[138:141], v[128:131], v[96:111]
	ds_read_b128 v[128:131], v160
	v_mfma_f32_32x32x16_bf16 v[80:95], v[134:137], v[142:145], v[80:95]
	v_mfma_f32_32x32x16_bf16 v[48:63], v[134:137], v[146:149], v[48:63]
	v_mfma_f32_32x32x16_bf16 v[16:31], v[134:137], v[150:153], v[16:31]
	v_mfma_f32_32x32x16_bf16 v[64:79], v[138:141], v[142:145], v[64:79]
	v_mfma_f32_32x32x16_bf16 v[32:47], v[138:141], v[146:149], v[32:47]
	v_mfma_f32_32x32x16_bf16 v[0:15], v[138:141], v[150:153], v[0:15]
	ds_read_b128 v[132:135], v161 offset:8192
	ds_read_b128 v[136:139], v160 offset:2048
	ds_read_b128 v[140:143], v161 offset:10240
	ds_read_b128 v[144:147], v161 offset:12288
	ds_read_b128 v[148:151], v161 offset:14336
	s_waitcnt vmcnt(0)
	s_barrier
	s_waitcnt lgkmcnt(0)
	v_mfma_f32_32x32x16_bf16 v[112:127], v[128:131], v[132:135], v[112:127]
	v_mfma_f32_32x32x16_bf16 v[80:95], v[128:131], v[140:143], v[80:95]
	v_mfma_f32_32x32x16_bf16 v[48:63], v[128:131], v[144:147], v[48:63]
	v_mfma_f32_32x32x16_bf16 v[16:31], v[128:131], v[148:151], v[16:31]
	v_mfma_f32_32x32x16_bf16 v[96:111], v[136:139], v[132:135], v[96:111]
	v_mfma_f32_32x32x16_bf16 v[64:79], v[136:139], v[140:143], v[64:79]
	v_mfma_f32_32x32x16_bf16 v[32:47], v[136:139], v[144:147], v[32:47]
	ds_read_b128 v[128:131], v155 offset:24576
	ds_read_b128 v[132:135], v155 offset:26624
	ds_read_b128 v[140:143], v156 offset:32768
	ds_read_b128 v[144:147], v156 offset:34816
	ds_read_b128 v[152:155], v156 offset:36864
	ds_read_b128 v[156:159], v156 offset:38912
	v_mfma_f32_32x32x16_bf16 v[0:15], v[136:139], v[148:151], v[0:15]
	s_waitcnt lgkmcnt(0)
	v_mfma_f32_32x32x16_bf16 v[112:127], v[128:131], v[140:143], v[112:127]
	s_cmp_lt_i32 s99, 2
	s_cselect_b64 s[40:41], -1, 0
	s_cmp_gt_i32 s99, 1
	s_mov_b64 s[6:7], -1
	v_mfma_f32_32x32x16_bf16 v[80:95], v[128:131], v[144:147], v[80:95]
	v_mfma_f32_32x32x16_bf16 v[48:63], v[128:131], v[152:155], v[48:63]
	v_mfma_f32_32x32x16_bf16 v[16:31], v[128:131], v[156:159], v[16:31]
	v_mfma_f32_32x32x16_bf16 v[96:111], v[132:135], v[140:143], v[96:111]
	v_mfma_f32_32x32x16_bf16 v[64:79], v[132:135], v[144:147], v[64:79]
	v_mfma_f32_32x32x16_bf16 v[32:47], v[132:135], v[152:155], v[32:47]
	v_mfma_f32_32x32x16_bf16 v[0:15], v[132:135], v[156:159], v[0:15]
	ds_read_b128 v[128:131], v160 offset:24576
	ds_read_b128 v[132:135], v161 offset:32768
	ds_read_b128 v[136:139], v160 offset:26624
	ds_read_b128 v[140:143], v161 offset:34816
	ds_read_b128 v[144:147], v161 offset:36864
	ds_read_b128 v[148:151], v161 offset:38912
	s_waitcnt vmcnt(0) lgkmcnt(0)
	s_barrier
	v_mfma_f32_32x32x16_bf16 v[112:127], v[128:131], v[132:135], v[112:127]
	v_mfma_f32_32x32x16_bf16 v[80:95], v[128:131], v[140:143], v[80:95]
	v_mfma_f32_32x32x16_bf16 v[48:63], v[128:131], v[144:147], v[48:63]
	v_mfma_f32_32x32x16_bf16 v[16:31], v[128:131], v[148:151], v[16:31]
	v_mfma_f32_32x32x16_bf16 v[96:111], v[136:139], v[132:135], v[96:111]
	v_mfma_f32_32x32x16_bf16 v[64:79], v[136:139], v[140:143], v[64:79]
	v_mfma_f32_32x32x16_bf16 v[32:47], v[136:139], v[144:147], v[32:47]
	v_mov_b32_e32 v145, v200
	v_mfma_f32_32x32x16_bf16 v[0:15], v[136:139], v[148:151], v[0:15]
	s_cbranch_scc0 .LBB0_223
	s_cmpk_gt_u32 s58, 0x1ff
	s_cbranch_scc0 .LBB0_220
	s_cmpk_lt_u32 s58, 0x400
	s_mov_b64 s[6:7], 0
	s_cbranch_scc1 .LBB0_214
	s_cmpk_gt_u32 s58, 0x57f
	s_mov_b64 s[42:43], -1
	s_cbranch_scc0 .LBB0_218
	s_cmpk_gt_u32 s58, 0x5ff
	s_mov_b64 s[34:35], -1
	s_cbranch_scc0 .LBB0_216
	s_cmpk_lt_u32 s58, 0x800
	s_mov_b64 s[34:35], 0
	s_cbranch_scc1 .LBB0_215
	s_cmpk_gt_u32 s58, 0x97f
	s_cbranch_scc0 .LBB0_212
	s_cmpk_gt_u32 s58, 0xaff
	s_mov_b64 s[42:43], 0
	s_cbranch_scc1 .LBB0_291
	s_load_dwordx2 s[4:5], s[0:1], 0x98
	v_readlane_b32 s8, v255, 36
	v_readlane_b32 s9, v255, 37
	s_lshl_b64 s[8:9], s[8:9], 2
	s_mov_b64 s[28:29], -1
	s_waitcnt lgkmcnt(0)
	s_add_u32 s4, s4, s8
	s_addc_u32 s5, s5, s9
	s_mov_b64 s[8:9], 0

; DI int otid() { int t = threadIdx.x; asm volatile("" : "+v"(t)); return t; }
; template <bool VMODE, int TJ>
; DI void gemm_mainloop(const bf16_t* __restrict__ W, const bf16_t* __restrict__ X, int NW, char* smem, f32x16 (&acc)[2][TJ]) {
;     constexpr int XROWS = 64 * TJ, STAGE = (128 + XROWS) * 64, NPW = 2 + TJ;
;     const int tid = otid(), lane = tid & 63, wave = tid >> 6, r = lane & 31, h = lane >> 5, wf = wave & 1, wt = wave >> 1;
;     const int goff = (16 * wave + (lane >> 2)) * 32 + (((lane & 3) ^ (lane >> 4)) << 3);
;     const bf16_t* wp = W + goff;
;     const bf16_t* xp = X + goff;
;     const size_t wks = (size_t)NW * 32, xks = (size_t)NTOK * 32;
;     char* ld = smem + tid * 16;
;     ...
;     const int xr = (r >> 2) & 3;
;     const int fo0 = r * 64 + (((0 + h) ^ xr) << 4), fo1 = r * 64 + (((2 + h) ^ xr) << 4);
;     __syncthreads();
; DI void inproj_phase(const Params& p, int l, char* smem) {
;     ...
;         const int n0 = nt * 128;
;         const bf16_t* W = p.wtin + (size_t)l * INW * D + (size_t)n0 * 32;
;         const bf16_t* X = p.hmix + (size_t)mtile * 256 * 32;
;         f32x16 acc[2][4];
;         zero_acc<4>(acc);
;         int vf0 = -1;
;         if (n0 >= 512 && n0 < 768) vf0 = n0 - 512;
;         else if (n0 >= 1536 && n0 < 1664) vf0 = 256 + (n0 - 1536);
;         else if (n0 >= 2816 && n0 < 3200) vf0 = 384 + (n0 - 2816);
;         if (vf0 >= 0) { gemm_mainloop<true, 4>(W, X, INW, smem, acc); epi_v(p, mtile, vf0, acc, smem); }
.LBB0_287:
	s_and_b64 vcc, exec, s[4:5]
	s_cbranch_vccz .LBB0_185
	v_mov_b32_e32 v4, v200
	s_movk_i32 s4, 0xffe0
	v_bfe_u32 v1, v4, 4, 2
	v_bitop3_b32 v1, v1, v4, 3 bitop3:0x78
	v_lshlrev_b32_e32 v0, 3, v4
	v_lshlrev_b32_e32 v1, 3, v1
	v_and_or_b32 v0, v0, s4, v1
	v_bfe_u32 v5, v4, 5, 1
	v_ashrrev_i32_e32 v1, 31, v0
	v_lshl_add_u32 v130, v4, 4, 32
	v_bfe_u32 v7, v4, 2, 2
	v_lshlrev_b64 v[128:129], 1, v[0:1]
	v_bitop3_b32 v9, v5, v7, 2 bitop3:0x36
	v_readfirstlane_b32 s5, v130
	v_add_u32_e32 v7, 0x1000, v130
	v_lshl_add_u64 v[0:1], s[52:53], 0, v[128:129]
	v_lshrrev_b32_e32 v6, 2, v4
	s_mov_b32 m0, s5
	v_readfirstlane_b32 s5, v7
	v_lshlrev_b32_e32 v8, 6, v4
	v_bitop3_b32 v6, v5, v6, 3 bitop3:0x78
	s_barrier
	global_load_lds_dwordx4 v[0:1], off
	v_lshl_add_u64 v[4:5], v[0:1], 0, s[26:27]
	s_mov_b32 m0, s5
	v_add_u32_e32 v7, 0x3000, v130
	global_load_lds_dwordx4 v[4:5], off
	v_add_u32_e32 v4, 0x2000, v130
	v_lshl_add_u64 v[2:3], s[56:57], 0, v[128:129]
	v_readfirstlane_b32 s5, v4
	s_mov_b32 m0, s5
	v_readfirstlane_b32 s5, v7
	v_add_u32_e32 v7, 0x4000, v130
	global_load_lds_dwordx4 v[2:3], off
	v_lshl_add_u64 v[4:5], v[2:3], 0, s[26:27]
	s_mov_b32 m0, s5
	v_readfirstlane_b32 s5, v7
	v_add_u32_e32 v7, 0x5000, v130
	global_load_lds_dwordx4 v[4:5], off
	v_lshl_add_u64 v[4:5], v[2:3], 0, s[16:17]
	s_mov_b32 m0, s5
	v_readfirstlane_b32 s5, v7
	v_add_u32_e32 v11, 0x6000, v130
	global_load_lds_dwordx4 v[4:5], off
	v_lshl_add_u64 v[4:5], v[2:3], 0, s[90:91]
	s_mov_b32 m0, s5
	s_mov_b64 s[6:7], 0x38000
	v_readfirstlane_b32 s5, v11
	global_load_lds_dwordx4 v[4:5], off
	v_lshl_add_u64 v[4:5], v[0:1], 0, s[6:7]
	s_mov_b32 m0, s5
	v_and_b32_e32 v10, 0x7c0, v8
	s_mov_b64 s[6:7], 0x120000
	global_load_lds_dwordx4 v[4:5], off
	v_add_u32_e32 v4, 0x7000, v130
	v_lshl_or_b32 v131, v6, 4, v10
	v_lshl_add_u64 v[6:7], v[2:3], 0, s[6:7]
	s_mov_b64 s[6:7], 0x39000
	v_readfirstlane_b32 s5, v4
	v_lshl_add_u64 v[0:1], v[0:1], 0, s[6:7]
	s_mov_b32 m0, s5
	v_add_u32_e32 v4, 0x9000, v130
	global_load_lds_dwordx4 v[0:1], off
	v_add_u32_e32 v0, 0x8000, v130
	s_mov_b64 s[6:7], 0x121000
	v_readfirstlane_b32 s5, v0
	s_mov_b32 m0, s5
	v_readfirstlane_b32 s5, v4
	v_add_u32_e32 v4, 0xa000, v130
	global_load_lds_dwordx4 v[6:7], off
	v_lshl_add_u64 v[0:1], v[2:3], 0, s[6:7]
	s_mov_b32 m0, s5
	s_mov_b64 s[6:7], 0x122000
	v_readfirstlane_b32 s5, v4
	global_load_lds_dwordx4 v[0:1], off
	v_lshl_add_u64 v[0:1], v[2:3], 0, s[6:7]
	s_mov_b32 m0, s5
	s_mov_b64 s[6:7], 0x123000
	global_load_lds_dwordx4 v[0:1], off
	v_lshl_add_u64 v[0:1], v[2:3], 0, s[6:7]
	v_add_u32_e32 v2, 0xb000, v130
	s_mov_b32 s4, 2
	v_readfirstlane_b32 s5, v2
	s_mov_b32 m0, s5
	v_lshl_or_b32 v132, v9, 4, v10
	global_load_lds_dwordx4 v[0:1], off
	v_mov_b32_e32 v0, 0
	v_and_b32_e32 v134, 0x1000, v8
	v_and_b32_e32 v133, 0xffffe000, v8
	s_mov_b32 s6, 0
	s_mov_b32 s5, 30
	v_mov_b32_e32 v1, v0
	v_mov_b32_e32 v2, v0
	v_mov_b32_e32 v3, v0
	v_mov_b32_e32 v4, v0
	v_mov_b32_e32 v5, v0
	v_mov_b32_e32 v6, v0
	v_mov_b32_e32 v7, v0
	v_mov_b32_e32 v8, v0
	v_mov_b32_e32 v9, v0
	v_mov_b32_e32 v10, v0
	v_mov_b32_e32 v11, v0
	v_mov_b32_e32 v12, v0
	v_mov_b32_e32 v13, v0
	v_mov_b32_e32 v14, v0
	v_mov_b32_e32 v15, v0
	v_mov_b32_e32 v16, v0
	v_mov_b32_e32 v17, v0
	v_mov_b32_e32 v18, v0
	v_mov_b32_e32 v19, v0
	v_mov_b32_e32 v20, v0
	v_mov_b32_e32 v21, v0
	v_mov_b32_e32 v22, v0
	v_mov_b32_e32 v23, v0
	v_mov_b32_e32 v24, v0
	v_mov_b32_e32 v25, v0
	v_mov_b32_e32 v26, v0
	v_mov_b32_e32 v27, v0
	v_mov_b32_e32 v28, v0
	v_mov_b32_e32 v29, v0
	v_mov_b32_e32 v30, v0
	v_mov_b32_e32 v31, v0
	v_mov_b32_e32 v32, v0
	v_mov_b32_e32 v33, v0
	v_mov_b32_e32 v34, v0
	v_mov_b32_e32 v35, v0
	v_mov_b32_e32 v36, v0
	v_mov_b32_e32 v37, v0
	v_mov_b32_e32 v38, v0
	v_mov_b32_e32 v39, v0
	v_mov_b32_e32 v40, v0
	v_mov_b32_e32 v41, v0
	v_mov_b32_e32 v42, v0
	v_mov_b32_e32 v43, v0
	v_mov_b32_e32 v44, v0
	v_mov_b32_e32 v45, v0
	v_mov_b32_e32 v46, v0
	v_mov_b32_e32 v47, v0
	v_mov_b32_e32 v48, v0
	v_mov_b32_e32 v49, v0
	v_mov_b32_e32 v50, v0
	v_mov_b32_e32 v51, v0
	v_mov_b32_e32 v52, v0
	v_mov_b32_e32 v53, v0
	v_mov_b32_e32 v54, v0
	v_mov_b32_e32 v55, v0
	v_mov_b32_e32 v56, v0
	v_mov_b32_e32 v57, v0
	v_mov_b32_e32 v58, v0
	v_mov_b32_e32 v59, v0
	v_mov_b32_e32 v60, v0
	v_mov_b32_e32 v61, v0
	v_mov_b32_e32 v62, v0
	v_mov_b32_e32 v63, v0
	v_mov_b32_e32 v64, v0
	v_mov_b32_e32 v65, v0
	v_mov_b32_e32 v66, v0
	v_mov_b32_e32 v67, v0
	v_mov_b32_e32 v68, v0
	v_mov_b32_e32 v69, v0
	v_mov_b32_e32 v70, v0
	v_mov_b32_e32 v71, v0
	v_mov_b32_e32 v72, v0
	v_mov_b32_e32 v73, v0
	v_mov_b32_e32 v74, v0
	v_mov_b32_e32 v75, v0
	v_mov_b32_e32 v76, v0
	v_mov_b32_e32 v77, v0
	v_mov_b32_e32 v78, v0
	v_mov_b32_e32 v79, v0
	v_mov_b32_e32 v80, v0
	v_mov_b32_e32 v81, v0
	v_mov_b32_e32 v82, v0
	v_mov_b32_e32 v83, v0
	v_mov_b32_e32 v84, v0
	v_mov_b32_e32 v85, v0
	v_mov_b32_e32 v86, v0
	v_mov_b32_e32 v87, v0
	v_mov_b32_e32 v88, v0
	v_mov_b32_e32 v89, v0
	v_mov_b32_e32 v90, v0
	v_mov_b32_e32 v91, v0
	v_mov_b32_e32 v92, v0
	v_mov_b32_e32 v93, v0
	v_mov_b32_e32 v94, v0
	v_mov_b32_e32 v95, v0
	v_mov_b32_e32 v96, v0
	v_mov_b32_e32 v97, v0
	v_mov_b32_e32 v98, v0
	v_mov_b32_e32 v99, v0
	v_mov_b32_e32 v100, v0
	v_mov_b32_e32 v101, v0
	v_mov_b32_e32 v102, v0
	v_mov_b32_e32 v103, v0
	v_mov_b32_e32 v104, v0
	v_mov_b32_e32 v105, v0
	v_mov_b32_e32 v106, v0
	v_mov_b32_e32 v107, v0
	v_mov_b32_e32 v108, v0
	v_mov_b32_e32 v109, v0
	v_mov_b32_e32 v110, v0
	v_mov_b32_e32 v111, v0
	v_mov_b32_e32 v112, v0
	v_mov_b32_e32 v113, v0
	v_mov_b32_e32 v114, v0
	v_mov_b32_e32 v115, v0
	v_mov_b32_e32 v116, v0
	v_mov_b32_e32 v117, v0
	v_mov_b32_e32 v118, v0
	v_mov_b32_e32 v119, v0
	v_mov_b32_e32 v120, v0
	v_mov_b32_e32 v121, v0
	v_mov_b32_e32 v122, v0
	v_mov_b32_e32 v123, v0
	v_mov_b32_e32 v124, v0
	v_mov_b32_e32 v125, v0
	v_mov_b32_e32 v126, v0
	v_mov_b32_e32 v127, v0
	v_readfirstlane_b32 s100, v130
	v_add_u32_e32 v170, 0x38000, v128
	v_add_u32_e32 v171, 0x39000, v128
	v_add_u32_e32 v172, 0x120000, v128
	v_add_u32_e32 v173, 0x121000, v128
	v_add_u32_e32 v174, 0x122000, v128
	v_add_u32_e32 v175, 0x123000, v128
	s_mul_i32 s7, s6, 0x6000
	s_add_i32 s7, s7, 32
	v_add_u32_e32 v135, s7, v134
	v_add_u32_e32 v168, s7, v133
	v_add_u32_e32 v140, v135, v131
	v_add_u32_e32 v156, v168, v131
	s_waitcnt vmcnt(6)
	s_barrier
; #define MFMA(a, b, c) __builtin_amdgcn_mfma_f32_32x32x16_bf16((a), (b), (c), 0, 0, 0)
; #define G_ISSUE(ks_, buf_) do { \
;     const bf16_t* wq_ = wp + (ks_) * wks; const bf16_t* xq_ = xp + (ks_) * xks; char* lb_ = ld + (buf_) * STAGE; \
;     dma16(wq_, lb_); dma16(wq_ + 2048, lb_ + 4096); \
;     _Pragma("unroll") for (int i_ = 0; i_ < TJ; ++i_) dma16(xq_ + i_ * 2048, lb_ + 8192 + i_ * 4096); } while (0)
; template <bool VMODE, int TJ>
; DI void gemm_mainloop(const bf16_t* __restrict__ W, const bf16_t* __restrict__ X, int NW, char* smem, f32x16 (&acc)[2][TJ]) {
;     ...
;         for (int ks = 0; ks < 32; ++ks) {
;             if (ks < 31) asm volatile("s_waitcnt vmcnt(6)" ::: "memory");
;             else asm volatile("s_waitcnt vmcnt(0)" ::: "memory");
;             __builtin_amdgcn_s_barrier();
;             const char* sw = smem + bc * STAGE + wf * 64 * 64;
;             const char* sx = smem + bc * STAGE + 8192 + wt * (32 * TJ) * 64;
;             bf16x8 fw[2], fx[TJ], gw[2], gx[TJ];
; #pragma unroll
;             for (int i = 0; i < 2; ++i) fw[i] = *(const bf16x8*)(sw + i * 32 * 64 + fo0);
; #pragma unroll
;             for (int j = 0; j < TJ; ++j) fx[j] = *(const bf16x8*)(sx + j * 32 * 64 + fo0);
;             __builtin_amdgcn_sched_barrier(0);
;             if (ks + 2 < 32) G_ISSUE(ks + 2, bn);
;             __builtin_amdgcn_sched_barrier(0);
; #pragma unroll
;             for (int i = 0; i < 2; ++i) gw[i] = *(const bf16x8*)(sw + i * 32 * 64 + fo1);
; #pragma unroll
;             for (int j = 0; j < TJ; ++j) gx[j] = *(const bf16x8*)(sx + j * 32 * 64 + fo1);
; #pragma unroll
;             for (int i = 0; i < 2; ++i)
; #pragma unroll
;                 for (int j = 0; j < TJ; ++j) acc[i][j] = VMODE ? MFMA(fx[j], fw[i], acc[i][j]) : MFMA(fw[i], fx[j], acc[i][j]);
; #pragma unroll
;             for (int i = 0; i < 2; ++i)
; #pragma unroll
;                 for (int j = 0; j < TJ; ++j) acc[i][j] = VMODE ? MFMA(gx[j], gw[i], acc[i][j]) : MFMA(gw[i], gx[j], acc[i][j]);
;             bc = (bc == 2) ? 0 : bc + 1; bn = (bn == 2) ? 0 : bn + 1;
;         }
	ds_read_b128 v[136:139], v140
	ds_read_b128 v[140:143], v140 offset:2048
	ds_read_b128 v[144:147], v156 offset:8192
	ds_read_b128 v[148:151], v156 offset:10240
	ds_read_b128 v[152:155], v156 offset:12288
	ds_read_b128 v[156:159], v156 offset:14336
	s_mul_i32 s7, s4, 0x6000
	s_add_i32 s101, s7, s100
	s_add_i32 s7, s6, 1
	s_cmp_lg_u32 s6, 2
	s_cselect_b32 s6, s7, 0
	s_add_i32 s7, s4, 1
	s_cmp_lg_u32 s4, 2
	s_cselect_b32 s4, s7, 0
	s_add_i32 s5, s5, -1
	s_add_u32 s56, s56, 0x120000
	s_addc_u32 s57, s57, 0
	s_add_u32 s52, s52, 0x38000
	s_addc_u32 s53, s53, 0
	v_add_u32_e32 v169, v135, v132
	v_add_u32_e32 v192, v168, v132
	s_mov_b32 m0, s101
	s_waitcnt lgkmcnt(0)
	v_mfma_f32_32x32x16_bf16 v[112:127], v[144:147], v[136:139], v[112:127]
	global_load_lds_dwordx4 v170, s[52:53]
	s_add_u32 m0, s101, 0x1000
	ds_read_b128 v[160:163], v192 offset:8192
	v_mfma_f32_32x32x16_bf16 v[96:111], v[148:151], v[136:139], v[96:111]
	global_load_lds_dwordx4 v171, s[52:53]
	s_add_u32 m0, s101, 0x2000
	ds_read_b128 v[164:167], v169
	v_mfma_f32_32x32x16_bf16 v[80:95], v[152:155], v[136:139], v[80:95]
	global_load_lds_dwordx4 v172, s[56:57]
	s_add_u32 m0, s101, 0x3000
	ds_read_b128 v[176:179], v169 offset:2048
	v_mfma_f32_32x32x16_bf16 v[64:79], v[156:159], v[136:139], v[64:79]
	global_load_lds_dwordx4 v173, s[56:57]
	s_add_u32 m0, s101, 0x4000
	ds_read_b128 v[180:183], v192 offset:10240
	v_mfma_f32_32x32x16_bf16 v[48:63], v[144:147], v[140:143], v[48:63]
	global_load_lds_dwordx4 v174, s[56:57]
	s_add_u32 m0, s101, 0x5000
	ds_read_b128 v[184:187], v192 offset:12288
	v_mfma_f32_32x32x16_bf16 v[32:47], v[148:151], v[140:143], v[32:47]
	global_load_lds_dwordx4 v175, s[56:57]
	ds_read_b128 v[188:191], v192 offset:14336
	v_mfma_f32_32x32x16_bf16 v[16:31], v[152:155], v[140:143], v[16:31]
	v_mfma_f32_32x32x16_bf16 v[0:15], v[156:159], v[140:143], v[0:15]
.LBB0_289:
	s_mul_i32 s7, s6, 0x6000
	s_add_i32 s7, s7, 32
	v_add_u32_e32 v135, s7, v134
	v_add_u32_e32 v168, s7, v133
	v_add_u32_e32 v140, v135, v131
	v_add_u32_e32 v156, v168, v131
	s_waitcnt vmcnt(6)
	s_waitcnt lgkmcnt(0)
	s_barrier
	ds_read_b128 v[136:139], v140
	ds_read_b128 v[140:143], v140 offset:2048
	ds_read_b128 v[144:147], v156 offset:8192
	ds_read_b128 v[148:151], v156 offset:10240
	ds_read_b128 v[152:155], v156 offset:12288
	ds_read_b128 v[156:159], v156 offset:14336
	s_mul_i32 s7, s4, 0x6000
	s_add_i32 s101, s7, s100
	s_add_i32 s7, s6, 1
	s_cmp_lg_u32 s6, 2
	s_cselect_b32 s6, s7, 0
	s_add_i32 s7, s4, 1
	s_cmp_lg_u32 s4, 2
	s_cselect_b32 s4, s7, 0
	s_add_i32 s5, s5, -1
	s_add_u32 s56, s56, 0x120000
	s_addc_u32 s57, s57, 0
	s_add_u32 s52, s52, 0x38000
	s_addc_u32 s53, s53, 0
	v_add_u32_e32 v169, v135, v132
	v_add_u32_e32 v192, v168, v132
	s_mov_b32 m0, s101
	v_mfma_f32_32x32x16_bf16 v[112:127], v[160:163], v[164:167], v[112:127]
	global_load_lds_dwordx4 v170, s[52:53]
	s_add_u32 m0, s101, 0x1000
	v_mfma_f32_32x32x16_bf16 v[96:111], v[180:183], v[164:167], v[96:111]
	global_load_lds_dwordx4 v171, s[52:53]
	s_add_u32 m0, s101, 0x2000
	v_mfma_f32_32x32x16_bf16 v[80:95], v[184:187], v[164:167], v[80:95]
	global_load_lds_dwordx4 v172, s[56:57]
	s_add_u32 m0, s101, 0x3000
	v_mfma_f32_32x32x16_bf16 v[64:79], v[188:191], v[164:167], v[64:79]
	global_load_lds_dwordx4 v173, s[56:57]
	s_add_u32 m0, s101, 0x4000
	v_mfma_f32_32x32x16_bf16 v[48:63], v[160:163], v[176:179], v[48:63]
	global_load_lds_dwordx4 v174, s[56:57]
	s_add_u32 m0, s101, 0x5000
	v_mfma_f32_32x32x16_bf16 v[32:47], v[180:183], v[176:179], v[32:47]
	global_load_lds_dwordx4 v175, s[56:57]
	v_mfma_f32_32x32x16_bf16 v[16:31], v[184:187], v[176:179], v[16:31]
	v_mfma_f32_32x32x16_bf16 v[0:15], v[188:191], v[176:179], v[0:15]
	s_waitcnt lgkmcnt(0)
	v_mfma_f32_32x32x16_bf16 v[112:127], v[144:147], v[136:139], v[112:127]
	ds_read_b128 v[160:163], v192 offset:8192
	v_mfma_f32_32x32x16_bf16 v[96:111], v[148:151], v[136:139], v[96:111]
	ds_read_b128 v[164:167], v169
	v_mfma_f32_32x32x16_bf16 v[80:95], v[152:155], v[136:139], v[80:95]
	ds_read_b128 v[176:179], v169 offset:2048
	v_mfma_f32_32x32x16_bf16 v[64:79], v[156:159], v[136:139], v[64:79]
	ds_read_b128 v[180:183], v192 offset:10240
	v_mfma_f32_32x32x16_bf16 v[48:63], v[144:147], v[140:143], v[48:63]
	ds_read_b128 v[184:187], v192 offset:12288
	v_mfma_f32_32x32x16_bf16 v[32:47], v[148:151], v[140:143], v[32:47]
	ds_read_b128 v[188:191], v192 offset:14336
	v_mfma_f32_32x32x16_bf16 v[16:31], v[152:155], v[140:143], v[16:31]
	v_mfma_f32_32x32x16_bf16 v[0:15], v[156:159], v[140:143], v[0:15]
	s_cmp_lg_u32 s5, 0
	s_cbranch_scc1 .LBB0_289
	s_waitcnt lgkmcnt(0)
	v_mfma_f32_32x32x16_bf16 v[112:127], v[160:163], v[164:167], v[112:127]
	v_mfma_f32_32x32x16_bf16 v[96:111], v[180:183], v[164:167], v[96:111]
	v_mfma_f32_32x32x16_bf16 v[80:95], v[184:187], v[164:167], v[80:95]
	v_mfma_f32_32x32x16_bf16 v[64:79], v[188:191], v[164:167], v[64:79]
	v_mfma_f32_32x32x16_bf16 v[48:63], v[160:163], v[176:179], v[48:63]
	v_mfma_f32_32x32x16_bf16 v[32:47], v[180:183], v[176:179], v[32:47]
	v_mfma_f32_32x32x16_bf16 v[16:31], v[184:187], v[176:179], v[16:31]
	v_mfma_f32_32x32x16_bf16 v[0:15], v[188:191], v[176:179], v[0:15]
	v_add_u32_e32 v154, 32, v134
	v_add_u32_e32 v133, 32, v133
	v_add_u32_e32 v155, v154, v131
	v_add_u32_e32 v156, v133, v131
	s_waitcnt vmcnt(6)
	s_barrier
; template <bool VMODE, int TJ>
; DI void gemm_mainloop(const bf16_t* __restrict__ W, const bf16_t* __restrict__ X, int NW, char* smem, f32x16 (&acc)[2][TJ]) {
;     ...
;         for (int ks = 0; ks < 32; ++ks) {
;             if (ks < 31) asm volatile("s_waitcnt vmcnt(6)" ::: "memory");
;             else asm volatile("s_waitcnt vmcnt(0)" ::: "memory");
;             __builtin_amdgcn_s_barrier();
;             const char* sw = smem + bc * STAGE + wf * 64 * 64;
;             const char* sx = smem + bc * STAGE + 8192 + wt * (32 * TJ) * 64;
;             bf16x8 fw[2], fx[TJ], gw[2], gx[TJ];
; #pragma unroll
;             for (int i = 0; i < 2; ++i) fw[i] = *(const bf16x8*)(sw + i * 32 * 64 + fo0);
; #pragma unroll
;             for (int j = 0; j < TJ; ++j) fx[j] = *(const bf16x8*)(sx + j * 32 * 64 + fo0);
;             __builtin_amdgcn_sched_barrier(0);
;             if (ks + 2 < 32) G_ISSUE(ks + 2, bn);
;             __builtin_amdgcn_sched_barrier(0);
; #pragma unroll
;             for (int i = 0; i < 2; ++i) gw[i] = *(const bf16x8*)(sw + i * 32 * 64 + fo1);
; #pragma unroll
;             for (int j = 0; j < TJ; ++j) gx[j] = *(const bf16x8*)(sx + j * 32 * 64 + fo1);
; #pragma unroll
;             for (int i = 0; i < 2; ++i)
; #pragma unroll
;                 for (int j = 0; j < TJ; ++j) acc[i][j] = VMODE ? MFMA(fx[j], fw[i], acc[i][j]) : MFMA(fw[i], fx[j], acc[i][j]);
; #pragma unroll
;             for (int i = 0; i < 2; ++i)
; #pragma unroll
;                 for (int j = 0; j < TJ; ++j) acc[i][j] = VMODE ? MFMA(gx[j], gw[i], acc[i][j]) : MFMA(gw[i], gx[j], acc[i][j]);
;             bc = (bc == 2) ? 0 : bc + 1; bn = (bn == 2) ? 0 : bn + 1;
;         }
;     }
; DI void epi_v(const Params& p, int mtile, int vf0, f32x16 (&acc)[2][4], char* smem) {
;     const int tid = otid(), lane = tid & 63, wave = tid >> 6, r = lane & 31, h = lane >> 5, wf = wave & 1, wt = wave >> 1;
;     const int b = mtile / 9, t0 = (mtile % 9) * 256;
;     char* sb = smem + wave * 16384;
; #pragma unroll
;     for (int i = 0; i < 2; ++i)
; #pragma unroll
;         for (int j = 0; j < 4; ++j)
; #pragma unroll
;             for (int q = 0; q < 4; ++q) {
;                 uint2 o; o.x = pk2(acc[i][j][4 * q], acc[i][j][4 * q + 1]); o.y = pk2(acc[i][j][4 * q + 2], acc[i][j][4 * q + 3]);
;                 stage_quad_bf16(sb + (j >> 1) * 8192, 32 * i + r, 4 * (j & 1) + 2 * (q >> 1) + h, q & 1, o);
	ds_read_b128 v[134:137], v155
	ds_read_b128 v[138:141], v155 offset:2048
	ds_read_b128 v[128:131], v156 offset:8192
	ds_read_b128 v[142:145], v156 offset:10240
	ds_read_b128 v[146:149], v156 offset:12288
	ds_read_b128 v[150:153], v156 offset:14336
	v_add_u32_e32 v172, v133, v132
	s_waitcnt lgkmcnt(0)
	v_mfma_f32_32x32x16_bf16 v[112:127], v[128:131], v[134:137], v[112:127]
	v_add_u32_e32 v160, v154, v132
	v_mfma_f32_32x32x16_bf16 v[48:63], v[128:131], v[138:141], v[48:63]
	ds_read_b128 v[128:131], v172 offset:8192
	v_mfma_f32_32x32x16_bf16 v[96:111], v[142:145], v[134:137], v[96:111]
	v_mfma_f32_32x32x16_bf16 v[80:95], v[146:149], v[134:137], v[80:95]
	v_mfma_f32_32x32x16_bf16 v[64:79], v[150:153], v[134:137], v[64:79]
	v_mfma_f32_32x32x16_bf16 v[32:47], v[142:145], v[138:141], v[32:47]
	v_mfma_f32_32x32x16_bf16 v[16:31], v[146:149], v[138:141], v[16:31]
	v_mfma_f32_32x32x16_bf16 v[0:15], v[150:153], v[138:141], v[0:15]
	ds_read_b128 v[132:135], v160
	ds_read_b128 v[136:139], v160 offset:2048
	ds_read_b128 v[140:143], v172 offset:10240
	ds_read_b128 v[144:147], v172 offset:12288
	ds_read_b128 v[148:151], v172 offset:14336
	s_waitcnt vmcnt(0)
	s_barrier
	s_waitcnt lgkmcnt(0)
	v_mfma_f32_32x32x16_bf16 v[112:127], v[128:131], v[132:135], v[112:127]
	v_mfma_f32_32x32x16_bf16 v[96:111], v[140:143], v[132:135], v[96:111]
	v_mfma_f32_32x32x16_bf16 v[80:95], v[144:147], v[132:135], v[80:95]
	v_mfma_f32_32x32x16_bf16 v[64:79], v[148:151], v[132:135], v[64:79]
	v_mfma_f32_32x32x16_bf16 v[48:63], v[128:131], v[136:139], v[48:63]
	v_mfma_f32_32x32x16_bf16 v[32:47], v[140:143], v[136:139], v[32:47]
	v_mfma_f32_32x32x16_bf16 v[16:31], v[144:147], v[136:139], v[16:31]
	ds_read_b128 v[128:131], v155 offset:24576
	ds_read_b128 v[132:135], v155 offset:26624
	ds_read_b128 v[140:143], v156 offset:32768
	ds_read_b128 v[144:147], v156 offset:34816
	ds_read_b128 v[152:155], v156 offset:36864
	ds_read_b128 v[156:159], v156 offset:38912
	v_mfma_f32_32x32x16_bf16 v[0:15], v[148:151], v[136:139], v[0:15]
	s_waitcnt lgkmcnt(0)
	v_mfma_f32_32x32x16_bf16 v[112:127], v[140:143], v[128:131], v[112:127]
	ds_read_b128 v[136:139], v160 offset:24576
	ds_read_b128 v[148:151], v160 offset:26624
	ds_read_b128 v[160:163], v172 offset:32768
	ds_read_b128 v[164:167], v172 offset:34816
	ds_read_b128 v[168:171], v172 offset:36864
	ds_read_b128 v[172:175], v172 offset:38912
	s_waitcnt vmcnt(0) lgkmcnt(0)
	s_barrier
	s_lshr_b32 s4, s47, 31
	s_ashr_i32 s5, s47, 1
	s_add_i32 s6, s5, s4
	v_mfma_f32_32x32x16_bf16 v[96:111], v[144:147], v[128:131], v[96:111]
	s_mul_i32 s4, s6, 9
	s_sub_i32 s8, s50, s4
	s_mul_hi_i32 s7, s6, 12
	s_mul_i32 s6, s6, 12
	s_lshr_b32 s9, s46, 6
	s_add_u32 s6, s6, s9
	s_addc_u32 s7, s7, 0
	v_mfma_f32_32x32x16_bf16 v[0:15], v[156:159], v[132:135], v[0:15]
	v_mfma_f32_32x32x16_bf16 v[112:127], v[160:163], v[136:139], v[112:127]
	v_mfma_f32_32x32x16_bf16 v[96:111], v[164:167], v[136:139], v[96:111]
	s_nop 10
	v_cvt_pk_bf16_f32 v112, v112, v113
	v_cvt_pk_bf16_f32 v113, v114, v115
	v_cvt_pk_bf16_f32 v115, v118, v119
	v_mfma_f32_32x32x16_bf16 v[32:47], v[144:147], v[132:135], v[32:47]
	v_cvt_pk_bf16_f32 v96, v96, v97
	v_cvt_pk_bf16_f32 v97, v98, v99
	v_cvt_pk_bf16_f32 v99, v102, v103
	v_mfma_f32_32x32x16_bf16 v[80:95], v[152:155], v[128:131], v[80:95]
	v_mfma_f32_32x32x16_bf16 v[64:79], v[156:159], v[128:131], v[64:79]
	v_mov_b32_e32 v128, v200
	s_load_dwordx2 s[4:5], s[0:1], 0xc8
	v_ashrrev_i32_e32 v130, 6, v128
	v_bfe_u32 v131, v128, 5, 1
	v_bitop3_b32 v114, v131, v128, 7 bitop3:0x78
	v_and_b32_e32 v192, 1, v130
	v_mfma_f32_32x32x16_bf16 v[0:15], v[172:175], v[148:151], v[0:15]
	v_and_b32_e32 v129, 63, v128
	v_mfma_f32_32x32x16_bf16 v[48:63], v[140:143], v[132:135], v[48:63]
	s_nop 9
	v_cvt_pk_bf16_f32 v0, v0, v1
	v_cvt_pk_bf16_f32 v1, v2, v3
	v_cvt_pk_bf16_f32 v2, v4, v5
	v_cvt_pk_bf16_f32 v3, v6, v7
	v_bfe_u32 v6, v128, 3, 3
	v_mfma_f32_32x32x16_bf16 v[16:31], v[152:155], v[132:135], v[16:31]
	v_lshlrev_b32_e32 v133, 7, v128
	v_lshl_add_u32 v132, v130, 14, 32
	v_and_b32_e32 v133, 0xf80, v133
	v_add_u32_e32 v133, v132, v133
	v_and_b32_e32 v134, 7, v128
	v_lshl_add_u32 v135, v114, 4, v133
	v_cvt_pk_bf16_f32 v114, v116, v117
	ds_write_b128 v135, v[112:115]
	v_bitop3_b32 v114, v131, v134, 2 bitop3:0x36
	v_cvt_pk_bf16_f32 v112, v120, v121
	v_cvt_pk_bf16_f32 v113, v122, v123
	v_lshl_add_u32 v116, v114, 4, v133
	v_cvt_pk_bf16_f32 v114, v124, v125
	v_cvt_pk_bf16_f32 v115, v126, v127
	v_bitop3_b32 v98, v131, v134, 4 bitop3:0x36
	v_mfma_f32_32x32x16_bf16 v[32:47], v[164:167], v[148:151], v[32:47]
	ds_write_b128 v116, v[112:115]
	v_lshl_add_u32 v112, v98, 4, v133
	v_cvt_pk_bf16_f32 v98, v100, v101
	ds_write_b128 v112, v[96:99]
	v_bitop3_b32 v98, v131, v134, 6 bitop3:0x36
	v_lshl_add_u32 v100, v98, 4, v133
	ds_write_b128 v112, v[0:3] offset:12288
	v_cvt_pk_bf16_f32 v0, v8, v9
	v_cvt_pk_bf16_f32 v1, v10, v11
	v_cvt_pk_bf16_f32 v2, v12, v13
	v_cvt_pk_bf16_f32 v3, v14, v15
	v_mfma_f32_32x32x16_bf16 v[16:31], v[168:171], v[148:151], v[16:31]
	ds_write_b128 v100, v[0:3] offset:12288
	v_and_b32_e32 v2, -2, v130
	v_lshl_add_u32 v2, s8, 2, v2
	v_lshl_add_u64 v[0:1], s[6:7], 0, v[192:193]
	v_ashrrev_i32_e32 v3, 31, v2
	v_mad_u64_u32 v[2:3], s[6:7], v0, 36, v[2:3]
	v_cvt_pk_bf16_f32 v96, v104, v105
	v_cvt_pk_bf16_f32 v97, v106, v107
	v_cvt_pk_bf16_f32 v98, v108, v109
	v_cvt_pk_bf16_f32 v99, v110, v111
	v_mad_i32_i24 v3, v1, 36, v3
	ds_write_b128 v100, v[96:99]
	v_cvt_pk_bf16_f32 v32, v32, v33
	v_cvt_pk_bf16_f32 v33, v34, v35
	v_cvt_pk_bf16_f32 v34, v36, v37
	v_lshlrev_b64 v[0:1], 13, v[2:3]
	v_lshl_add_u32 v37, v129, 4, v132
	s_waitcnt lgkmcnt(0)
; DI unsigned pk2(float a, float b) { f2_t v = {a, b}; bf2_t r = __builtin_convertvector(v, bf2_t); return __builtin_bit_cast(unsigned, r); }
; DI int otid() { int t = threadIdx.x; asm volatile("" : "+v"(t)); return t; }
; template <int NIT>
; DI void stage_flush_bf16(const char* sb, bf16_t* gdst, int lane) {
; #pragma unroll
;     for (int it = 0; it < NIT; ++it) {
;         const int c = lane + 64 * it, row = c >> 3, lc = (c & 7) ^ (row & 7);
;         const u32x4_t v = *(const u32x4_t*)(sb + c * 16);
;         *(u32x4_t*)(gdst + row * 64 + lc * 8) = v;
;     }
; }
; DI void epi_v(const Params& p, int mtile, int vf0, f32x16 (&acc)[2][4], char* smem) {
;     const int tid = otid(), lane = tid & 63, wave = tid >> 6, r = lane & 31, h = lane >> 5, wf = wave & 1, wt = wave >> 1;
;     const int b = mtile / 9, t0 = (mtile % 9) * 256;
;     char* sb = smem + wave * 16384;
; #pragma unroll
;     for (int i = 0; i < 2; ++i)
; #pragma unroll
;         for (int j = 0; j < 4; ++j)
; #pragma unroll
;             for (int q = 0; q < 4; ++q) {
;                 uint2 o; o.x = pk2(acc[i][j][4 * q], acc[i][j][4 * q + 1]); o.y = pk2(acc[i][j][4 * q + 2], acc[i][j][4 * q + 3]);
;                 stage_quad_bf16(sb + (j >> 1) * 8192, 32 * i + r, 4 * (j & 1) + 2 * (q >> 1) + h, q & 1, o);
;             }
;     bf16_t* g0 = p.vT + (((size_t)b * 12 + (vf0 >> 6) + wf) * 36 + (t0 >> 6) + 2 * wt) * 4096;
;     stage_flush_bf16<8>(sb, g0, lane);
;     stage_flush_bf16<8>(sb + 8192, g0 + 4096, lane);
; }
	v_lshl_add_u64 v[4:5], s[4:5], 0, v[0:1]
	ds_read_b128 v[0:3], v37
	v_xor_b32_e32 v8, v6, v128
	v_cvt_pk_bf16_f32 v16, v16, v17
	v_cvt_pk_bf16_f32 v17, v18, v19
	v_cvt_pk_bf16_f32 v18, v20, v21
	v_cvt_pk_bf16_f32 v19, v22, v23
	v_lshlrev_b32_e32 v192, 7, v6
	v_lshlrev_b32_e32 v8, 4, v8
	ds_write_b128 v135, v[16:19] offset:12288
	v_cvt_pk_bf16_f32 v19, v30, v31
	v_lshl_add_u64 v[6:7], v[4:5], 0, v[192:193]
	v_and_b32_e32 v30, 0x70, v8
	v_mov_b32_e32 v31, v193
	v_lshl_add_u64 v[6:7], v[6:7], 0, v[30:31]
	v_cvt_pk_bf16_f32 v35, v38, v39
	s_waitcnt lgkmcnt(1)
	global_store_dwordx4 v[6:7], v[0:3], off
	ds_write_b128 v112, v[32:35] offset:4096
	v_cvt_pk_bf16_f32 v34, v44, v45
	v_or_b32_e32 v0, 64, v129
	v_lshl_add_u32 v44, v0, 4, v132
	v_lshrrev_b32_e32 v6, 3, v0
	ds_read_b128 v[0:3], v44
	v_xor_b32_e32 v8, v6, v128
	v_cvt_pk_bf16_f32 v17, v26, v27
	v_lshlrev_b32_e32 v26, 7, v6
	v_mov_b32_e32 v27, v193
	v_lshlrev_b32_e32 v8, 4, v8
	v_cvt_pk_bf16_f32 v18, v28, v29
	v_lshl_add_u64 v[6:7], v[4:5], 0, v[26:27]
	v_and_b32_e32 v28, 0x70, v8
	v_mov_b32_e32 v29, v193
	v_lshl_add_u64 v[6:7], v[6:7], 0, v[28:29]
	s_waitcnt lgkmcnt(0)
	global_store_dwordx4 v[6:7], v[0:3], off
	v_mov_b32_e32 v23, v193
	v_mfma_f32_32x32x16_bf16 v[48:63], v[160:163], v[148:151], v[48:63]
	v_or_b32_e32 v0, 0x80, v129
	v_lshl_add_u32 v45, v0, 4, v132
	v_lshrrev_b32_e32 v6, 3, v0
	ds_read_b128 v[0:3], v45
	v_xor_b32_e32 v8, v6, v128
	v_lshlrev_b32_e32 v22, 7, v6
	v_lshlrev_b32_e32 v8, 4, v8
	v_cvt_pk_bf16_f32 v16, v24, v25
	v_lshl_add_u64 v[6:7], v[4:5], 0, v[22:23]
	v_and_b32_e32 v24, 0x70, v8
	v_mov_b32_e32 v25, v193
	v_lshl_add_u64 v[6:7], v[6:7], 0, v[24:25]
	s_waitcnt lgkmcnt(0)
	global_store_dwordx4 v[6:7], v[0:3], off
	ds_write_b128 v116, v[16:19] offset:12288
	v_mov_b32_e32 v19, v193
	v_or_b32_e32 v0, 0xc0, v129
	v_lshl_add_u32 v36, v0, 4, v132
	v_lshrrev_b32_e32 v6, 3, v0
	ds_read_b128 v[0:3], v36
	v_xor_b32_e32 v8, v6, v128
	v_lshlrev_b32_e32 v18, 7, v6
	v_lshlrev_b32_e32 v8, 4, v8
	v_lshl_add_u64 v[6:7], v[4:5], 0, v[18:19]
	v_and_b32_e32 v20, 0x70, v8
	v_mov_b32_e32 v21, v193
	v_cvt_pk_bf16_f32 v48, v48, v49
	v_cvt_pk_bf16_f32 v49, v50, v51
	v_cvt_pk_bf16_f32 v50, v52, v53
	v_cvt_pk_bf16_f32 v51, v54, v55
	v_lshl_add_u64 v[6:7], v[6:7], 0, v[20:21]
	ds_write_b128 v135, v[48:51] offset:4096
	v_cvt_pk_bf16_f32 v48, v56, v57
	v_cvt_pk_bf16_f32 v49, v58, v59
	v_cvt_pk_bf16_f32 v50, v60, v61
	v_cvt_pk_bf16_f32 v51, v62, v63
	v_cvt_pk_bf16_f32 v32, v40, v41
	v_cvt_pk_bf16_f32 v33, v42, v43
	v_cvt_pk_bf16_f32 v35, v46, v47
	s_waitcnt lgkmcnt(1)
	global_store_dwordx4 v[6:7], v[0:3], off
	ds_write_b128 v116, v[48:51] offset:4096
	ds_write_b128 v100, v[32:35] offset:4096
	v_or_b32_e32 v0, 0x100, v129
	v_lshl_add_u32 v35, v0, 4, v132
	v_lshrrev_b32_e32 v6, 3, v0
	ds_read_b128 v[0:3], v35
	v_xor_b32_e32 v8, v6, v128
	v_lshlrev_b32_e32 v14, 7, v6
	v_mov_b32_e32 v15, v193
	v_lshlrev_b32_e32 v8, 4, v8
	v_lshl_add_u64 v[6:7], v[4:5], 0, v[14:15]
	v_and_b32_e32 v16, 0x70, v8
	v_mov_b32_e32 v17, v193
	v_lshl_add_u64 v[6:7], v[6:7], 0, v[16:17]
	s_waitcnt lgkmcnt(0)
	global_store_dwordx4 v[6:7], v[0:3], off
	v_mov_b32_e32 v11, v193
	v_mov_b32_e32 v13, v193
	v_or_b32_e32 v0, 0x140, v129
	v_lshl_add_u32 v34, v0, 4, v132
	v_lshrrev_b32_e32 v6, 3, v0
	ds_read_b128 v[0:3], v34
	v_xor_b32_e32 v8, v6, v128
	v_lshlrev_b32_e32 v10, 7, v6
	v_lshlrev_b32_e32 v8, 4, v8
	v_lshl_add_u64 v[6:7], v[4:5], 0, v[10:11]
	v_and_b32_e32 v12, 0x70, v8
	v_lshl_add_u64 v[6:7], v[6:7], 0, v[12:13]
	s_waitcnt lgkmcnt(0)
	global_store_dwordx4 v[6:7], v[0:3], off
	v_mfma_f32_32x32x16_bf16 v[80:95], v[168:171], v[136:139], v[80:95]
	v_mov_b32_e32 v7, v193
	v_or_b32_e32 v0, 0x180, v129
	v_lshl_add_u32 v33, v0, 4, v132
	v_lshrrev_b32_e32 v6, 3, v0
	ds_read_b128 v[0:3], v33
	v_xor_b32_e32 v8, v6, v128
	v_lshlrev_b32_e32 v6, 7, v6
	v_mfma_f32_32x32x16_bf16 v[64:79], v[172:175], v[136:139], v[64:79]
	v_lshlrev_b32_e32 v8, 4, v8
	v_lshl_add_u64 v[38:39], v[4:5], 0, v[6:7]
	v_and_b32_e32 v8, 0x70, v8
	v_mov_b32_e32 v9, v193
	v_lshl_add_u64 v[38:39], v[38:39], 0, v[8:9]
	s_waitcnt lgkmcnt(0)
	global_store_dwordx4 v[38:39], v[0:3], off
	v_cvt_pk_bf16_f32 v80, v80, v81
	v_cvt_pk_bf16_f32 v81, v82, v83
	v_or_b32_e32 v0, 0x1c0, v129
	v_lshl_add_u32 v32, v0, 4, v132
	v_lshrrev_b32_e32 v1, 3, v0
	ds_read_b128 v[38:41], v32
	v_xor_b32_e32 v2, v1, v128
	v_cvt_pk_bf16_f32 v82, v84, v85
	v_cvt_pk_bf16_f32 v83, v86, v87
	v_cvt_pk_bf16_f32 v64, v64, v65
	v_cvt_pk_bf16_f32 v65, v66, v67
	v_cvt_pk_bf16_f32 v66, v68, v69
	v_cvt_pk_bf16_f32 v67, v70, v71
	v_lshlrev_b32_e32 v0, 7, v1
	v_mov_b32_e32 v1, v193
	v_lshlrev_b32_e32 v2, 4, v2
	ds_write_b128 v135, v[80:83] offset:8192
	v_cvt_pk_bf16_f32 v80, v88, v89
	v_cvt_pk_bf16_f32 v81, v90, v91
	v_cvt_pk_bf16_f32 v82, v92, v93
	v_cvt_pk_bf16_f32 v83, v94, v95
	ds_write_b128 v112, v[64:67] offset:8192
	v_cvt_pk_bf16_f32 v64, v72, v73
	v_cvt_pk_bf16_f32 v65, v74, v75
	v_cvt_pk_bf16_f32 v66, v76, v77
	v_cvt_pk_bf16_f32 v67, v78, v79
	v_lshl_add_u64 v[42:43], v[4:5], 0, v[0:1]
	v_and_b32_e32 v2, 0x70, v2
	v_mov_b32_e32 v3, v193
	ds_write_b128 v116, v[80:83] offset:8192
	ds_write_b128 v100, v[64:67] offset:8192
	v_lshl_add_u64 v[42:43], v[42:43], 0, v[2:3]
	s_waitcnt lgkmcnt(4)
	global_store_dwordx4 v[42:43], v[38:41], off
	ds_read_b128 v[38:41], v37 offset:8192
	v_lshl_add_u64 v[4:5], v[4:5], 0, s[16:17]
	v_lshl_add_u64 v[42:43], v[4:5], 0, v[192:193]
	v_lshl_add_u64 v[30:31], v[42:43], 0, v[30:31]
	v_lshl_add_u64 v[26:27], v[4:5], 0, v[26:27]
	s_waitcnt lgkmcnt(0)
	global_store_dwordx4 v[30:31], v[38:41], off
	ds_read_b128 v[38:41], v44 offset:8192
	v_lshl_add_u64 v[26:27], v[26:27], 0, v[28:29]
	v_lshl_add_u64 v[22:23], v[4:5], 0, v[22:23]
	v_lshl_add_u64 v[22:23], v[22:23], 0, v[24:25]
	v_lshl_add_u64 v[18:19], v[4:5], 0, v[18:19]
	s_waitcnt lgkmcnt(0)
	global_store_dwordx4 v[26:27], v[38:41], off
	ds_read_b128 v[26:29], v45 offset:8192
	v_lshl_add_u64 v[18:19], v[18:19], 0, v[20:21]
	v_lshl_add_u64 v[14:15], v[4:5], 0, v[14:15]
	v_lshl_add_u64 v[14:15], v[14:15], 0, v[16:17]
	v_lshl_add_u64 v[10:11], v[4:5], 0, v[10:11]
	s_waitcnt lgkmcnt(0)
	global_store_dwordx4 v[22:23], v[26:29], off
	ds_read_b128 v[22:25], v36 offset:8192
	v_lshl_add_u64 v[10:11], v[10:11], 0, v[12:13]
	v_lshl_add_u64 v[6:7], v[4:5], 0, v[6:7]
	v_lshl_add_u64 v[6:7], v[6:7], 0, v[8:9]
	v_lshl_add_u64 v[0:1], v[4:5], 0, v[0:1]
	s_waitcnt lgkmcnt(0)
	global_store_dwordx4 v[18:19], v[22:25], off
	ds_read_b128 v[18:21], v35 offset:8192
	v_lshl_add_u64 v[0:1], v[0:1], 0, v[2:3]
	s_waitcnt lgkmcnt(0)
	global_store_dwordx4 v[14:15], v[18:21], off
	ds_read_b128 v[14:17], v34 offset:8192
	s_waitcnt lgkmcnt(0)
	global_store_dwordx4 v[10:11], v[14:17], off
	ds_read_b128 v[10:13], v33 offset:8192
	s_waitcnt lgkmcnt(0)
	global_store_dwordx4 v[6:7], v[10:13], off
	ds_read_b128 v[6:9], v32 offset:8192
	s_waitcnt lgkmcnt(0)
	global_store_dwordx4 v[0:1], v[6:9], off
	s_branch .LBB0_185
